# speedup vs baseline: 1.0553x; 1.0553x over previous
; #define WAIT_V(n) asm volatile("s_waitcnt vmcnt(%0)" ::"n"(n) : "memory")
;     ...
;     for (int t = 0; t < nt; ++t) {
;       const int cur = t & 1;
;       const char* sa = shm + cur * STAGE_B;
;       const char* sn = shm + (cur ^ 1) * STAGE_B;
;       const bool more = (t + 1 < nt) || (nitem < ntiles);
; #pragma unroll
;       for (int ks = 0; ks < 2; ++ks) {
; #pragma unroll
;         for (int p = 0; p < NP; ++p) {
;           const int q = ks * NP + p;
;           acc[p * 2][0] = __builtin_amdgcn_mfma_f32_16x16x32_bf16(Bq[BDBL ? ks : 0][0], Aq[q & 1][0], acc[p * 2][0], 0, 0, 0);
;           __builtin_amdgcn_sched_barrier(0);
;           if (q == 2 * NP - 1) {
;             WAIT_V(0);
;             __syncthreads();
;             if (more) {
;               if constexpr (BDBL) {
; #pragma unroll
;                 for (int n = 0; n < 4; ++n) Bq[0][n] = *(const bf16x8*)(sn + boff + (n * 2 + 0) * 1024);
;               }
; #pragma unroll
;               for (int i = 0; i < 2; ++i) Aq[0][i] = *(const bf16x8*)(sn + aoff + (i * 2 + 0) * 1024);
;             }
;           } else if (p + 1 < NP) {
; #pragma unroll
;             for (int i = 0; i < 2; ++i) Aq[(q + 1) & 1][i] = *(const bf16x8*)(sa + aoff + (((p + 1) * 2 + i) * 2 + ks) * 1024);
;           } else {
;             if constexpr (BDBL) {
; #pragma unroll
;               for (int n = 0; n < 4; ++n) Bq[1][n] = *(const bf16x8*)(sa + boff + (n * 2 + 1) * 1024);
;             }
; #pragma unroll
;             for (int i = 0; i < 2; ++i) Aq[(q + 1) & 1][i] = *(const bf16x8*)(sa + aoff + (i * 2 + 1) * 1024);
;           }
;           __builtin_amdgcn_sched_barrier(0);
; #pragma unroll
;           for (int i = 0; i < 2; ++i)
; #pragma unroll
;             for (int n = 0; n < 4; ++n)
;               if (i + n > 0)
;                 acc[p * 2 + i][n] = __builtin_amdgcn_mfma_f32_16x16x32_bf16(Bq[BDBL ? ks : 0][n], Aq[q & 1][i], acc[p * 2 + i][n], 0, 0, 0);
;           __builtin_amdgcn_sched_barrier(0);
;           if (q == GLDS_AT) {
;             if (t + 1 < nt) GLDS_STAGE(cur ^ 1, t + 1, Ab, Bb);
;             else if (nitem < ntiles) GLDS_STAGE(0, 0, nAb, nBb);
;             __builtin_amdgcn_sched_barrier(0);
;           }
.LBB0_186:
	s_waitcnt lgkmcnt(0)
	s_nop 0
	v_mfma_f32_16x16x32_bf16 v[148:151], v[12:15], v[20:23], v[148:151]
	s_and_b32 s16, s51, 0x10000
	s_xor_b32 s17, s16, 0x10000
	v_add_u32_e32 v184, s16, v220
	v_or_b32_e32 v176, s16, v221
	v_bitop3_b32 v185, s51, v221, v233 bitop3:0xce
	v_add_u32_e32 v186, s17, v220
	ds_read_b128 v[156:159], v184 offset:4096
	ds_read_b128 v[160:163], v184 offset:6144
	v_mfma_f32_16x16x32_bf16 v[144:147], v[8:11], v[20:23], v[144:147]
	s_add_i32 s16, s17, s19
	v_lshl_add_u64 v[180:181], v[152:153], 0, s[0:1]
	v_mfma_f32_16x16x32_bf16 v[140:143], v[4:7], v[20:23], v[140:143]
	v_lshl_add_u64 v[182:183], v[180:181], 0, s[38:39]
	s_mov_b32 m0, s16
	v_mfma_f32_16x16x32_bf16 v[20:23], v[0:3], v[20:23], v[136:139]
	s_add_i32 s17, s16, 0x8000
	global_load_lds_dwordx4 v[182:183], off
	v_mfma_f32_16x16x32_bf16 v[132:135], v[12:15], v[16:19], v[132:135]
	v_lshl_add_u64 v[182:183], v[180:181], 0, s[82:83]
	s_add_i32 m0, s16, 0x2000
	v_mfma_f32_16x16x32_bf16 v[128:131], v[8:11], v[16:19], v[128:131]
	global_load_lds_dwordx4 v[182:183], off
	v_lshl_add_u64 v[182:183], v[180:181], 0, s[78:79]
	v_mfma_f32_16x16x32_bf16 v[124:127], v[4:7], v[16:19], v[124:127]
	s_add_i32 m0, s16, 0x4000
	v_lshl_add_u64 v[180:181], v[180:181], 0, s[2:3]
	v_mfma_f32_16x16x32_bf16 v[16:19], v[0:3], v[16:19], v[120:123]
	global_load_lds_dwordx4 v[182:183], off
	s_add_i32 m0, s16, 0x6000
	s_waitcnt lgkmcnt(1)
	v_mfma_f32_16x16x32_bf16 v[116:119], v[12:15], v[156:159], v[116:119]
	s_nop 0
	ds_read_b128 v[120:123], v184 offset:8192
	ds_read_b128 v[136:139], v184 offset:10240
	global_load_lds_dwordx4 v[180:181], off
	v_lshl_add_u64 v[180:181], v[154:155], 0, s[0:1]
	v_mfma_f32_16x16x32_bf16 v[112:115], v[8:11], v[156:159], v[112:115]
	v_lshl_add_u64 v[182:183], v[180:181], 0, s[38:39]
	s_mov_b32 m0, s17
	v_mfma_f32_16x16x32_bf16 v[108:111], v[4:7], v[156:159], v[108:111]
	global_load_lds_dwordx4 v[182:183], off
	v_lshl_add_u64 v[182:183], v[180:181], 0, s[82:83]
	v_mfma_f32_16x16x32_bf16 v[104:107], v[0:3], v[156:159], v[104:107]
	s_add_i32 m0, s16, 0xa000
	s_waitcnt lgkmcnt(2)
	v_mfma_f32_16x16x32_bf16 v[100:103], v[12:15], v[160:163], v[100:103]
	global_load_lds_dwordx4 v[182:183], off
	v_lshl_add_u64 v[182:183], v[180:181], 0, s[78:79]
	v_mfma_f32_16x16x32_bf16 v[96:99], v[8:11], v[160:163], v[96:99]
	s_add_i32 m0, s16, 0xc000
	v_lshl_add_u64 v[180:181], v[180:181], 0, s[2:3]
	v_mfma_f32_16x16x32_bf16 v[92:95], v[4:7], v[160:163], v[92:95]
	global_load_lds_dwordx4 v[182:183], off
	s_add_i32 m0, s16, 0xe000
	v_mfma_f32_16x16x32_bf16 v[88:91], v[0:3], v[160:163], v[88:91]
	global_load_lds_dwordx4 v[180:181], off
	s_waitcnt lgkmcnt(1)
	v_mfma_f32_16x16x32_bf16 v[84:87], v[12:15], v[120:123], v[84:87]
	ds_read_b128 v[156:159], v184 offset:12288
	ds_read_b128 v[160:163], v184 offset:14336
	v_mfma_f32_16x16x32_bf16 v[80:83], v[8:11], v[120:123], v[80:83]
	v_mfma_f32_16x16x32_bf16 v[76:79], v[4:7], v[120:123], v[76:79]
	v_mfma_f32_16x16x32_bf16 v[72:75], v[0:3], v[120:123], v[72:75]
	s_waitcnt lgkmcnt(2)
	v_mfma_f32_16x16x32_bf16 v[68:71], v[12:15], v[136:139], v[68:71]
	v_mfma_f32_16x16x32_bf16 v[64:67], v[8:11], v[136:139], v[64:67]
	v_mfma_f32_16x16x32_bf16 v[60:63], v[4:7], v[136:139], v[60:63]
	v_mfma_f32_16x16x32_bf16 v[56:59], v[0:3], v[136:139], v[56:59]
	s_waitcnt lgkmcnt(1)
	v_mfma_f32_16x16x32_bf16 v[52:55], v[12:15], v[156:159], v[52:55]
	ds_read_b128 v[164:167], v176 offset:33792
	ds_read_b128 v[168:171], v176 offset:35840
	ds_read_b128 v[172:175], v176 offset:37888
	ds_read_b128 v[176:179], v176 offset:39936
	ds_read_b128 v[120:123], v184 offset:1024
	ds_read_b128 v[180:183], v184 offset:3072
	v_mfma_f32_16x16x32_bf16 v[48:51], v[8:11], v[156:159], v[48:51]
	v_mfma_f32_16x16x32_bf16 v[44:47], v[4:7], v[156:159], v[44:47]
	v_mfma_f32_16x16x32_bf16 v[40:43], v[0:3], v[156:159], v[40:43]
	s_waitcnt lgkmcnt(6)
	v_mfma_f32_16x16x32_bf16 v[36:39], v[12:15], v[160:163], v[36:39]
	v_mfma_f32_16x16x32_bf16 v[32:35], v[8:11], v[160:163], v[32:35]
	v_mfma_f32_16x16x32_bf16 v[28:31], v[4:7], v[160:163], v[28:31]
	v_mfma_f32_16x16x32_bf16 v[24:27], v[0:3], v[160:163], v[24:27]
	s_waitcnt lgkmcnt(0)
	v_mfma_f32_16x16x32_bf16 v[148:151], v[164:167], v[120:123], v[148:151]
	ds_read_b128 v[0:3], v184 offset:5120
	ds_read_b128 v[4:7], v184 offset:7168
	v_mfma_f32_16x16x32_bf16 v[144:147], v[168:171], v[120:123], v[144:147]
	v_mfma_f32_16x16x32_bf16 v[140:143], v[172:175], v[120:123], v[140:143]
	v_mfma_f32_16x16x32_bf16 v[136:139], v[176:179], v[120:123], v[20:23]
	v_mfma_f32_16x16x32_bf16 v[132:135], v[164:167], v[180:183], v[132:135]
	v_mfma_f32_16x16x32_bf16 v[128:131], v[168:171], v[180:183], v[128:131]
	v_mfma_f32_16x16x32_bf16 v[124:127], v[172:175], v[180:183], v[124:127]
	v_mfma_f32_16x16x32_bf16 v[120:123], v[176:179], v[180:183], v[16:19]
	s_waitcnt lgkmcnt(1)
	v_mfma_f32_16x16x32_bf16 v[116:119], v[164:167], v[0:3], v[116:119]
	ds_read_b128 v[8:11], v184 offset:9216
	ds_read_b128 v[12:15], v184 offset:11264
	v_mfma_f32_16x16x32_bf16 v[112:115], v[168:171], v[0:3], v[112:115]
	v_mfma_f32_16x16x32_bf16 v[108:111], v[172:175], v[0:3], v[108:111]
	v_mfma_f32_16x16x32_bf16 v[104:107], v[176:179], v[0:3], v[104:107]
	s_waitcnt lgkmcnt(2)
	v_mfma_f32_16x16x32_bf16 v[100:103], v[164:167], v[4:7], v[100:103]
	v_mfma_f32_16x16x32_bf16 v[96:99], v[168:171], v[4:7], v[96:99]
	v_mfma_f32_16x16x32_bf16 v[92:95], v[172:175], v[4:7], v[92:95]
	v_mfma_f32_16x16x32_bf16 v[88:91], v[176:179], v[4:7], v[88:91]
	s_waitcnt lgkmcnt(1)
	v_mfma_f32_16x16x32_bf16 v[84:87], v[164:167], v[8:11], v[84:87]
	ds_read_b128 v[156:159], v184 offset:13312
	ds_read_b128 v[160:163], v184 offset:15360
	v_mfma_f32_16x16x32_bf16 v[80:83], v[168:171], v[8:11], v[80:83]
	v_mfma_f32_16x16x32_bf16 v[76:79], v[172:175], v[8:11], v[76:79]
	v_mfma_f32_16x16x32_bf16 v[72:75], v[176:179], v[8:11], v[72:75]
	s_waitcnt lgkmcnt(2)
	v_mfma_f32_16x16x32_bf16 v[68:71], v[164:167], v[12:15], v[68:71]
	v_mfma_f32_16x16x32_bf16 v[64:67], v[168:171], v[12:15], v[64:67]
	v_mfma_f32_16x16x32_bf16 v[60:63], v[172:175], v[12:15], v[60:63]
	v_mfma_f32_16x16x32_bf16 v[56:59], v[176:179], v[12:15], v[56:59]
	s_waitcnt lgkmcnt(1)
	v_mfma_f32_16x16x32_bf16 v[52:55], v[164:167], v[156:159], v[52:55]
	s_waitcnt vmcnt(0)
	s_waitcnt lgkmcnt(0)
	s_barrier
; #define WAIT_V(n) asm volatile("s_waitcnt vmcnt(%0)" ::"n"(n) : "memory")
;     ...
;     for (int t = 0; t < nt; ++t) {
;       const int cur = t & 1;
;       const char* sa = shm + cur * STAGE_B;
;       const char* sn = shm + (cur ^ 1) * STAGE_B;
;       const bool more = (t + 1 < nt) || (nitem < ntiles);
; #pragma unroll
;       for (int ks = 0; ks < 2; ++ks) {
; #pragma unroll
;         for (int p = 0; p < NP; ++p) {
;           const int q = ks * NP + p;
;           acc[p * 2][0] = __builtin_amdgcn_mfma_f32_16x16x32_bf16(Bq[BDBL ? ks : 0][0], Aq[q & 1][0], acc[p * 2][0], 0, 0, 0);
;           __builtin_amdgcn_sched_barrier(0);
;           if (q == 2 * NP - 1) {
;             WAIT_V(0);
;             __syncthreads();
;             if (more) {
;               if constexpr (BDBL) {
; #pragma unroll
;                 for (int n = 0; n < 4; ++n) Bq[0][n] = *(const bf16x8*)(sn + boff + (n * 2 + 0) * 1024);
;               }
; #pragma unroll
;               for (int i = 0; i < 2; ++i) Aq[0][i] = *(const bf16x8*)(sn + aoff + (i * 2 + 0) * 1024);
;             }
;           } else if (p + 1 < NP) {
; #pragma unroll
;             for (int i = 0; i < 2; ++i) Aq[(q + 1) & 1][i] = *(const bf16x8*)(sa + aoff + (((p + 1) * 2 + i) * 2 + ks) * 1024);
;           } else {
;             if constexpr (BDBL) {
; #pragma unroll
;               for (int n = 0; n < 4; ++n) Bq[1][n] = *(const bf16x8*)(sa + boff + (n * 2 + 1) * 1024);
;             }
; #pragma unroll
;             for (int i = 0; i < 2; ++i) Aq[(q + 1) & 1][i] = *(const bf16x8*)(sa + aoff + (i * 2 + 1) * 1024);
;           }
;           __builtin_amdgcn_sched_barrier(0);
; #pragma unroll
;           for (int i = 0; i < 2; ++i)
; #pragma unroll
;             for (int n = 0; n < 4; ++n)
;               if (i + n > 0)
;                 acc[p * 2 + i][n] = __builtin_amdgcn_mfma_f32_16x16x32_bf16(Bq[BDBL ? ks : 0][n], Aq[q & 1][i], acc[p * 2 + i][n], 0, 0, 0);
;           __builtin_amdgcn_sched_barrier(0);
;           if (q == GLDS_AT) {
;             if (t + 1 < nt) GLDS_STAGE(cur ^ 1, t + 1, Ab, Bb);
;             else if (nitem < ntiles) GLDS_STAGE(0, 0, nAb, nBb);
;             __builtin_amdgcn_sched_barrier(0);
;           }
	ds_read_b128 v[12:15], v185 offset:32768
	ds_read_b128 v[8:11], v185 offset:34816
	ds_read_b128 v[4:7], v185 offset:36864
	ds_read_b128 v[0:3], v185 offset:38912
	ds_read_b128 v[20:23], v186
	ds_read_b128 v[16:19], v186 offset:2048
	v_mfma_f32_16x16x32_bf16 v[48:51], v[168:171], v[156:159], v[48:51]
	v_mfma_f32_16x16x32_bf16 v[44:47], v[172:175], v[156:159], v[44:47]
	v_mfma_f32_16x16x32_bf16 v[40:43], v[176:179], v[156:159], v[40:43]
	v_mfma_f32_16x16x32_bf16 v[36:39], v[164:167], v[160:163], v[36:39]
	v_mfma_f32_16x16x32_bf16 v[32:35], v[168:171], v[160:163], v[32:35]
	v_mfma_f32_16x16x32_bf16 v[28:31], v[172:175], v[160:163], v[28:31]
	v_mfma_f32_16x16x32_bf16 v[24:27], v[176:179], v[160:163], v[24:27]
	s_add_u32 s0, s0, 0x80
	s_addc_u32 s1, s1, 0
	s_add_i32 s51, s51, 0x10000
	s_cmpk_eq_i32 s0, 0x780
	s_cbranch_scc0 .LBB0_186
	s_waitcnt lgkmcnt(1)
	v_mfma_f32_16x16x32_bf16 v[148:151], v[12:15], v[20:23], v[148:151]
	v_add_u32_e32 v226, 0x10000, v220
	ds_read_b128 v[152:155], v226 offset:4096
	ds_read_b128 v[156:159], v226 offset:6144
	v_mfma_f32_16x16x32_bf16 v[176:179], v[8:11], v[20:23], v[144:147]
	v_mfma_f32_16x16x32_bf16 v[180:183], v[4:7], v[20:23], v[140:143]
	v_mfma_f32_16x16x32_bf16 v[20:23], v[0:3], v[20:23], v[136:139]
	s_waitcnt lgkmcnt(2)
	v_mfma_f32_16x16x32_bf16 v[132:135], v[12:15], v[16:19], v[132:135]
	v_mfma_f32_16x16x32_bf16 v[128:131], v[8:11], v[16:19], v[128:131]
	v_mfma_f32_16x16x32_bf16 v[184:187], v[4:7], v[16:19], v[124:127]
	v_mfma_f32_16x16x32_bf16 v[16:19], v[0:3], v[16:19], v[120:123]
	s_waitcnt lgkmcnt(1)
	v_mfma_f32_16x16x32_bf16 v[116:119], v[12:15], v[152:155], v[116:119]
	s_nop 0
	ds_read_b128 v[120:123], v226 offset:8192
	ds_read_b128 v[124:127], v226 offset:10240
	v_mfma_f32_16x16x32_bf16 v[188:191], v[8:11], v[152:155], v[112:115]
	v_mfma_f32_16x16x32_bf16 v[192:195], v[4:7], v[152:155], v[108:111]
	v_mfma_f32_16x16x32_bf16 v[104:107], v[0:3], v[152:155], v[104:107]
	s_waitcnt lgkmcnt(2)
	v_mfma_f32_16x16x32_bf16 v[100:103], v[12:15], v[156:159], v[100:103]
	v_mfma_f32_16x16x32_bf16 v[96:99], v[8:11], v[156:159], v[96:99]
	v_mfma_f32_16x16x32_bf16 v[196:199], v[4:7], v[156:159], v[92:95]
	v_mfma_f32_16x16x32_bf16 v[88:91], v[0:3], v[156:159], v[88:91]
	s_waitcnt lgkmcnt(1)
	v_mfma_f32_16x16x32_bf16 v[84:87], v[12:15], v[120:123], v[84:87]
	ds_read_b128 v[92:95], v226 offset:12288
	ds_read_b128 v[108:111], v226 offset:14336
	v_mfma_f32_16x16x32_bf16 v[200:203], v[8:11], v[120:123], v[80:83]
	v_mfma_f32_16x16x32_bf16 v[204:207], v[4:7], v[120:123], v[76:79]
	v_mfma_f32_16x16x32_bf16 v[72:75], v[0:3], v[120:123], v[72:75]
	s_waitcnt lgkmcnt(2)
	v_mfma_f32_16x16x32_bf16 v[68:71], v[12:15], v[124:127], v[68:71]
	v_mfma_f32_16x16x32_bf16 v[64:67], v[8:11], v[124:127], v[64:67]
	v_mfma_f32_16x16x32_bf16 v[208:211], v[4:7], v[124:127], v[60:63]
	v_mfma_f32_16x16x32_bf16 v[56:59], v[0:3], v[124:127], v[56:59]
	s_waitcnt lgkmcnt(1)
	v_mfma_f32_16x16x32_bf16 v[212:215], v[12:15], v[92:95], v[52:55]
	s_nop 2
	v_add_u32_e32 v52, 0x10400, v222
	v_add_u32_e32 v53, 0x10c00, v222
	ds_read_b128 v[152:155], v52
	ds_read_b128 v[156:159], v53
	v_add_u32_e32 v52, 0x11400, v222
	v_add_u32_e32 v53, 0x11c00, v222
	ds_read_b128 v[160:163], v52
	ds_read_b128 v[164:167], v53
	ds_read_b128 v[76:79], v226 offset:1024
	ds_read_b128 v[60:63], v226 offset:3072
	v_mfma_f32_16x16x32_bf16 v[52:55], v[8:11], v[92:95], v[48:51]
	v_mfma_f32_16x16x32_bf16 v[168:171], v[4:7], v[92:95], v[44:47]
	v_mfma_f32_16x16x32_bf16 v[40:43], v[0:3], v[92:95], v[40:43]
	s_waitcnt lgkmcnt(6)
	v_mfma_f32_16x16x32_bf16 v[36:39], v[12:15], v[108:111], v[36:39]
	v_mfma_f32_16x16x32_bf16 v[32:35], v[8:11], v[108:111], v[32:35]
	v_mfma_f32_16x16x32_bf16 v[172:175], v[4:7], v[108:111], v[28:31]
	v_mfma_f32_16x16x32_bf16 v[24:27], v[0:3], v[108:111], v[24:27]
	s_nop 1
	v_cndmask_b32_e64 v28, 0, 1, s[14:15]
	v_cmp_ne_u32_e64 s[0:1], 1, v28
	s_andn2_b64 vcc, exec, s[14:15]
	s_cbranch_vccnz .LBB0_189
	s_mov_b32 m0, s19
	v_lshl_add_u64 v[28:29], s[6:7], 0, v[224:225]
	v_lshl_add_u64 v[44:45], v[28:29], 0, s[76:77]
	global_load_lds_dwordx4 v[28:29], off
	s_add_i32 m0, s19, 0x2000
	v_lshl_add_u64 v[46:47], v[28:29], 0, s[96:97]
	global_load_lds_dwordx4 v[44:45], off
	s_add_i32 m0, s19, 0x4000
	v_lshl_add_u64 v[48:49], v[28:29], 0, s[70:71]
	global_load_lds_dwordx4 v[46:47], off
	s_add_i32 m0, s19, 0x6000
	v_lshl_add_u64 v[30:31], s[10:11], 0, v[224:225]
	global_load_lds_dwordx4 v[48:49], off
	s_add_i32 m0, s19, 0x8000
	v_lshl_add_u64 v[50:51], v[30:31], 0, s[76:77]
	global_load_lds_dwordx4 v[30:31], off
	s_add_i32 m0, s19, 0xa000
	v_lshl_add_u64 v[80:81], v[30:31], 0, s[96:97]
	global_load_lds_dwordx4 v[50:51], off
	s_add_i32 m0, s19, 0xc000
	v_lshl_add_u64 v[82:83], v[30:31], 0, s[70:71]
	global_load_lds_dwordx4 v[80:81], off
	s_add_i32 m0, s19, 0xe000
	s_nop 0
	global_load_lds_dwordx4 v[82:83], off

; #define WAIT_V(n) asm volatile("s_waitcnt vmcnt(%0)" ::"n"(n) : "memory")
;     ...
;     for (int t = 0; t < nt; ++t) {
;       const int cur = t & 1;
;       const char* sa = shm + cur * STAGE_B;
;       const char* sn = shm + (cur ^ 1) * STAGE_B;
;       const bool more = (t + 1 < nt) || (nitem < ntiles);
; #pragma unroll
;       for (int ks = 0; ks < 2; ++ks) {
; #pragma unroll
;         for (int p = 0; p < NP; ++p) {
;           const int q = ks * NP + p;
;           acc[p * 2][0] = __builtin_amdgcn_mfma_f32_16x16x32_bf16(Bq[BDBL ? ks : 0][0], Aq[q & 1][0], acc[p * 2][0], 0, 0, 0);
;           __builtin_amdgcn_sched_barrier(0);
;           if (q == 2 * NP - 1) {
;             WAIT_V(0);
;             __syncthreads();
;             if (more) {
;               if constexpr (BDBL) {
; #pragma unroll
;                 for (int n = 0; n < 4; ++n) Bq[0][n] = *(const bf16x8*)(sn + boff + (n * 2 + 0) * 1024);
;               }
; #pragma unroll
;               for (int i = 0; i < 2; ++i) Aq[0][i] = *(const bf16x8*)(sn + aoff + (i * 2 + 0) * 1024);
;             }
;           } else if (p + 1 < NP) {
; #pragma unroll
;             for (int i = 0; i < 2; ++i) Aq[(q + 1) & 1][i] = *(const bf16x8*)(sa + aoff + (((p + 1) * 2 + i) * 2 + ks) * 1024);
;           } else {
;             if constexpr (BDBL) {
; #pragma unroll
;               for (int n = 0; n < 4; ++n) Bq[1][n] = *(const bf16x8*)(sa + boff + (n * 2 + 1) * 1024);
;             }
; #pragma unroll
;             for (int i = 0; i < 2; ++i) Aq[(q + 1) & 1][i] = *(const bf16x8*)(sa + aoff + (i * 2 + 1) * 1024);
;           }
;           __builtin_amdgcn_sched_barrier(0);
; #pragma unroll
;           for (int i = 0; i < 2; ++i)
; #pragma unroll
;             for (int n = 0; n < 4; ++n)
;               if (i + n > 0)
;                 acc[p * 2 + i][n] = __builtin_amdgcn_mfma_f32_16x16x32_bf16(Bq[BDBL ? ks : 0][n], Aq[q & 1][i], acc[p * 2 + i][n], 0, 0, 0);
;           __builtin_amdgcn_sched_barrier(0);
;           if (q == GLDS_AT) {
;             if (t + 1 < nt) GLDS_STAGE(cur ^ 1, t + 1, Ab, Bb);
;             else if (nitem < ntiles) GLDS_STAGE(0, 0, nAb, nBb);
;             __builtin_amdgcn_sched_barrier(0);
;           }
.LBB0_239:
	s_waitcnt lgkmcnt(0)
	s_nop 0
	v_mfma_f32_16x16x32_bf16 v[148:151], v[12:15], v[20:23], v[148:151]
	s_and_b32 s18, s50, 0x10000
	s_xor_b32 s19, s18, 0x10000
	v_add_u32_e32 v184, s18, v241
	v_or_b32_e32 v176, s18, v242
	v_bitop3_b32 v185, s50, v242, v233 bitop3:0xce
	v_add_u32_e32 v186, s19, v241
	ds_read_b128 v[156:159], v184 offset:4096
	ds_read_b128 v[160:163], v184 offset:6144
	v_mfma_f32_16x16x32_bf16 v[144:147], v[8:11], v[20:23], v[144:147]
	s_add_i32 s18, s19, s4
	v_lshl_add_u64 v[180:181], v[152:153], 0, s[0:1]
	v_mfma_f32_16x16x32_bf16 v[140:143], v[4:7], v[20:23], v[140:143]
	v_lshl_add_u64 v[182:183], v[180:181], 0, s[38:39]
	s_mov_b32 m0, s18
	v_mfma_f32_16x16x32_bf16 v[20:23], v[0:3], v[20:23], v[136:139]
	s_add_i32 s19, s18, 0x8000
	global_load_lds_dwordx4 v[182:183], off
	v_mfma_f32_16x16x32_bf16 v[132:135], v[12:15], v[16:19], v[132:135]
	v_lshl_add_u64 v[182:183], v[180:181], 0, s[72:73]
	s_add_i32 m0, s18, 0x2000
	v_mfma_f32_16x16x32_bf16 v[128:131], v[8:11], v[16:19], v[128:131]
	global_load_lds_dwordx4 v[182:183], off
	v_lshl_add_u64 v[182:183], v[180:181], 0, s[54:55]
	v_mfma_f32_16x16x32_bf16 v[124:127], v[4:7], v[16:19], v[124:127]
	s_add_i32 m0, s18, 0x4000
	v_lshl_add_u64 v[180:181], v[180:181], 0, s[80:81]
	v_mfma_f32_16x16x32_bf16 v[16:19], v[0:3], v[16:19], v[120:123]
	global_load_lds_dwordx4 v[182:183], off
	s_add_i32 m0, s18, 0x6000
	s_waitcnt lgkmcnt(1)
	v_mfma_f32_16x16x32_bf16 v[116:119], v[12:15], v[156:159], v[116:119]
	s_nop 0
	ds_read_b128 v[120:123], v184 offset:8192
	ds_read_b128 v[136:139], v184 offset:10240
	global_load_lds_dwordx4 v[180:181], off
	v_lshl_add_u64 v[180:181], v[154:155], 0, s[0:1]
	v_mfma_f32_16x16x32_bf16 v[112:115], v[8:11], v[156:159], v[112:115]
	v_lshl_add_u64 v[182:183], v[180:181], 0, s[38:39]
	s_mov_b32 m0, s19
	v_mfma_f32_16x16x32_bf16 v[108:111], v[4:7], v[156:159], v[108:111]
	global_load_lds_dwordx4 v[182:183], off
	v_lshl_add_u64 v[182:183], v[180:181], 0, s[72:73]
	v_mfma_f32_16x16x32_bf16 v[104:107], v[0:3], v[156:159], v[104:107]
	s_add_i32 m0, s18, 0xa000
	s_waitcnt lgkmcnt(2)
	v_mfma_f32_16x16x32_bf16 v[100:103], v[12:15], v[160:163], v[100:103]
	global_load_lds_dwordx4 v[182:183], off
	v_lshl_add_u64 v[182:183], v[180:181], 0, s[54:55]
	v_mfma_f32_16x16x32_bf16 v[96:99], v[8:11], v[160:163], v[96:99]
	s_add_i32 m0, s18, 0xc000
	v_lshl_add_u64 v[180:181], v[180:181], 0, s[80:81]
	v_mfma_f32_16x16x32_bf16 v[92:95], v[4:7], v[160:163], v[92:95]
	global_load_lds_dwordx4 v[182:183], off
	s_add_i32 m0, s18, 0xe000
	v_mfma_f32_16x16x32_bf16 v[88:91], v[0:3], v[160:163], v[88:91]
	global_load_lds_dwordx4 v[180:181], off
	s_waitcnt lgkmcnt(1)
	v_mfma_f32_16x16x32_bf16 v[84:87], v[12:15], v[120:123], v[84:87]
	ds_read_b128 v[156:159], v184 offset:12288
	ds_read_b128 v[160:163], v184 offset:14336
	v_mfma_f32_16x16x32_bf16 v[80:83], v[8:11], v[120:123], v[80:83]
	v_mfma_f32_16x16x32_bf16 v[76:79], v[4:7], v[120:123], v[76:79]
	v_mfma_f32_16x16x32_bf16 v[72:75], v[0:3], v[120:123], v[72:75]
	s_waitcnt lgkmcnt(2)
	v_mfma_f32_16x16x32_bf16 v[68:71], v[12:15], v[136:139], v[68:71]
	v_mfma_f32_16x16x32_bf16 v[64:67], v[8:11], v[136:139], v[64:67]
	v_mfma_f32_16x16x32_bf16 v[60:63], v[4:7], v[136:139], v[60:63]
	v_mfma_f32_16x16x32_bf16 v[56:59], v[0:3], v[136:139], v[56:59]
	s_waitcnt lgkmcnt(1)
	v_mfma_f32_16x16x32_bf16 v[52:55], v[12:15], v[156:159], v[52:55]
	ds_read_b128 v[164:167], v176 offset:33792
	ds_read_b128 v[168:171], v176 offset:35840
	ds_read_b128 v[172:175], v176 offset:37888
	ds_read_b128 v[176:179], v176 offset:39936
	ds_read_b128 v[120:123], v184 offset:1024
	ds_read_b128 v[180:183], v184 offset:3072
	v_mfma_f32_16x16x32_bf16 v[48:51], v[8:11], v[156:159], v[48:51]
	v_mfma_f32_16x16x32_bf16 v[44:47], v[4:7], v[156:159], v[44:47]
	v_mfma_f32_16x16x32_bf16 v[40:43], v[0:3], v[156:159], v[40:43]
	s_waitcnt lgkmcnt(6)
	v_mfma_f32_16x16x32_bf16 v[36:39], v[12:15], v[160:163], v[36:39]
	v_mfma_f32_16x16x32_bf16 v[32:35], v[8:11], v[160:163], v[32:35]
	v_mfma_f32_16x16x32_bf16 v[28:31], v[4:7], v[160:163], v[28:31]
	v_mfma_f32_16x16x32_bf16 v[24:27], v[0:3], v[160:163], v[24:27]
	s_waitcnt lgkmcnt(0)
	v_mfma_f32_16x16x32_bf16 v[148:151], v[164:167], v[120:123], v[148:151]
	ds_read_b128 v[0:3], v184 offset:5120
	ds_read_b128 v[4:7], v184 offset:7168
	v_mfma_f32_16x16x32_bf16 v[144:147], v[168:171], v[120:123], v[144:147]
	v_mfma_f32_16x16x32_bf16 v[140:143], v[172:175], v[120:123], v[140:143]
	v_mfma_f32_16x16x32_bf16 v[136:139], v[176:179], v[120:123], v[20:23]
	v_mfma_f32_16x16x32_bf16 v[132:135], v[164:167], v[180:183], v[132:135]
	v_mfma_f32_16x16x32_bf16 v[128:131], v[168:171], v[180:183], v[128:131]
	v_mfma_f32_16x16x32_bf16 v[124:127], v[172:175], v[180:183], v[124:127]
	v_mfma_f32_16x16x32_bf16 v[120:123], v[176:179], v[180:183], v[16:19]
	s_waitcnt lgkmcnt(1)
	v_mfma_f32_16x16x32_bf16 v[116:119], v[164:167], v[0:3], v[116:119]
	ds_read_b128 v[8:11], v184 offset:9216
	ds_read_b128 v[12:15], v184 offset:11264
	v_mfma_f32_16x16x32_bf16 v[112:115], v[168:171], v[0:3], v[112:115]
	v_mfma_f32_16x16x32_bf16 v[108:111], v[172:175], v[0:3], v[108:111]
	v_mfma_f32_16x16x32_bf16 v[104:107], v[176:179], v[0:3], v[104:107]
	s_waitcnt lgkmcnt(2)
	v_mfma_f32_16x16x32_bf16 v[100:103], v[164:167], v[4:7], v[100:103]
	v_mfma_f32_16x16x32_bf16 v[96:99], v[168:171], v[4:7], v[96:99]
	v_mfma_f32_16x16x32_bf16 v[92:95], v[172:175], v[4:7], v[92:95]
	v_mfma_f32_16x16x32_bf16 v[88:91], v[176:179], v[4:7], v[88:91]
	s_waitcnt lgkmcnt(1)
	v_mfma_f32_16x16x32_bf16 v[84:87], v[164:167], v[8:11], v[84:87]
	ds_read_b128 v[156:159], v184 offset:13312
	ds_read_b128 v[160:163], v184 offset:15360
	v_mfma_f32_16x16x32_bf16 v[80:83], v[168:171], v[8:11], v[80:83]
	v_mfma_f32_16x16x32_bf16 v[76:79], v[172:175], v[8:11], v[76:79]
	v_mfma_f32_16x16x32_bf16 v[72:75], v[176:179], v[8:11], v[72:75]
	s_waitcnt lgkmcnt(2)
	v_mfma_f32_16x16x32_bf16 v[68:71], v[164:167], v[12:15], v[68:71]
	v_mfma_f32_16x16x32_bf16 v[64:67], v[168:171], v[12:15], v[64:67]
	v_mfma_f32_16x16x32_bf16 v[60:63], v[172:175], v[12:15], v[60:63]
	v_mfma_f32_16x16x32_bf16 v[56:59], v[176:179], v[12:15], v[56:59]
	s_waitcnt lgkmcnt(1)
	v_mfma_f32_16x16x32_bf16 v[52:55], v[164:167], v[156:159], v[52:55]
	s_waitcnt vmcnt(0)
	s_waitcnt lgkmcnt(0)
	s_barrier
; #define WAIT_V(n) asm volatile("s_waitcnt vmcnt(%0)" ::"n"(n) : "memory")
;     ...
;     for (int t = 0; t < nt; ++t) {
;       const int cur = t & 1;
;       const char* sa = shm + cur * STAGE_B;
;       const char* sn = shm + (cur ^ 1) * STAGE_B;
;       const bool more = (t + 1 < nt) || (nitem < ntiles);
; #pragma unroll
;       for (int ks = 0; ks < 2; ++ks) {
; #pragma unroll
;         for (int p = 0; p < NP; ++p) {
;           const int q = ks * NP + p;
;           acc[p * 2][0] = __builtin_amdgcn_mfma_f32_16x16x32_bf16(Bq[BDBL ? ks : 0][0], Aq[q & 1][0], acc[p * 2][0], 0, 0, 0);
;           __builtin_amdgcn_sched_barrier(0);
;           if (q == 2 * NP - 1) {
;             WAIT_V(0);
;             __syncthreads();
;             if (more) {
;               if constexpr (BDBL) {
; #pragma unroll
;                 for (int n = 0; n < 4; ++n) Bq[0][n] = *(const bf16x8*)(sn + boff + (n * 2 + 0) * 1024);
;               }
; #pragma unroll
;               for (int i = 0; i < 2; ++i) Aq[0][i] = *(const bf16x8*)(sn + aoff + (i * 2 + 0) * 1024);
;             }
;           } else if (p + 1 < NP) {
; #pragma unroll
;             for (int i = 0; i < 2; ++i) Aq[(q + 1) & 1][i] = *(const bf16x8*)(sa + aoff + (((p + 1) * 2 + i) * 2 + ks) * 1024);
;           } else {
;             if constexpr (BDBL) {
; #pragma unroll
;               for (int n = 0; n < 4; ++n) Bq[1][n] = *(const bf16x8*)(sa + boff + (n * 2 + 1) * 1024);
;             }
; #pragma unroll
;             for (int i = 0; i < 2; ++i) Aq[(q + 1) & 1][i] = *(const bf16x8*)(sa + aoff + (i * 2 + 1) * 1024);
;           }
;           __builtin_amdgcn_sched_barrier(0);
; #pragma unroll
;           for (int i = 0; i < 2; ++i)
; #pragma unroll
;             for (int n = 0; n < 4; ++n)
;               if (i + n > 0)
;                 acc[p * 2 + i][n] = __builtin_amdgcn_mfma_f32_16x16x32_bf16(Bq[BDBL ? ks : 0][n], Aq[q & 1][i], acc[p * 2 + i][n], 0, 0, 0);
;           __builtin_amdgcn_sched_barrier(0);
;           if (q == GLDS_AT) {
;             if (t + 1 < nt) GLDS_STAGE(cur ^ 1, t + 1, Ab, Bb);
;             else if (nitem < ntiles) GLDS_STAGE(0, 0, nAb, nBb);
;             __builtin_amdgcn_sched_barrier(0);
;           }
	ds_read_b128 v[12:15], v185 offset:32768
	ds_read_b128 v[8:11], v185 offset:34816
	ds_read_b128 v[4:7], v185 offset:36864
	ds_read_b128 v[0:3], v185 offset:38912
	ds_read_b128 v[20:23], v186
	ds_read_b128 v[16:19], v186 offset:2048
	v_mfma_f32_16x16x32_bf16 v[48:51], v[168:171], v[156:159], v[48:51]
	v_mfma_f32_16x16x32_bf16 v[44:47], v[172:175], v[156:159], v[44:47]
	v_mfma_f32_16x16x32_bf16 v[40:43], v[176:179], v[156:159], v[40:43]
	v_mfma_f32_16x16x32_bf16 v[36:39], v[164:167], v[160:163], v[36:39]
	v_mfma_f32_16x16x32_bf16 v[32:35], v[168:171], v[160:163], v[32:35]
	v_mfma_f32_16x16x32_bf16 v[28:31], v[172:175], v[160:163], v[28:31]
	v_mfma_f32_16x16x32_bf16 v[24:27], v[176:179], v[160:163], v[24:27]
	s_add_u32 s0, s0, 0x80
	s_addc_u32 s1, s1, 0
	s_add_i32 s50, s50, 0x10000
	s_cmpk_eq_i32 s0, 0x1580
	s_cbranch_scc0 .LBB0_239
	s_waitcnt lgkmcnt(1)
	v_mfma_f32_16x16x32_bf16 v[148:151], v[12:15], v[20:23], v[148:151]
	v_add_u32_e32 v246, 0x10000, v241
	ds_read_b128 v[152:155], v246 offset:4096
	ds_read_b128 v[156:159], v246 offset:6144
	v_mfma_f32_16x16x32_bf16 v[144:147], v[8:11], v[20:23], v[144:147]
	v_mfma_f32_16x16x32_bf16 v[140:143], v[4:7], v[20:23], v[140:143]
	v_mfma_f32_16x16x32_bf16 v[20:23], v[0:3], v[20:23], v[136:139]
	s_waitcnt lgkmcnt(2)
	v_mfma_f32_16x16x32_bf16 v[132:135], v[12:15], v[16:19], v[132:135]
	v_mfma_f32_16x16x32_bf16 v[128:131], v[8:11], v[16:19], v[128:131]
	v_mfma_f32_16x16x32_bf16 v[124:127], v[4:7], v[16:19], v[124:127]
	v_mfma_f32_16x16x32_bf16 v[16:19], v[0:3], v[16:19], v[120:123]
	s_waitcnt lgkmcnt(1)
	v_mfma_f32_16x16x32_bf16 v[120:123], v[12:15], v[152:155], v[116:119]
	s_nop 2
	ds_read_b128 v[116:119], v246 offset:8192
	ds_read_b128 v[136:139], v246 offset:10240
	v_mfma_f32_16x16x32_bf16 v[176:179], v[8:11], v[152:155], v[112:115]
	v_mfma_f32_16x16x32_bf16 v[180:183], v[4:7], v[152:155], v[108:111]
	v_mfma_f32_16x16x32_bf16 v[184:187], v[0:3], v[152:155], v[104:107]
	s_waitcnt lgkmcnt(2)
	v_mfma_f32_16x16x32_bf16 v[100:103], v[12:15], v[156:159], v[100:103]
	v_mfma_f32_16x16x32_bf16 v[96:99], v[8:11], v[156:159], v[96:99]
	v_mfma_f32_16x16x32_bf16 v[92:95], v[4:7], v[156:159], v[92:95]
	v_mfma_f32_16x16x32_bf16 v[88:91], v[0:3], v[156:159], v[88:91]
	s_waitcnt lgkmcnt(1)
	v_mfma_f32_16x16x32_bf16 v[188:191], v[12:15], v[116:119], v[84:87]
	ds_read_b128 v[104:107], v246 offset:12288
	ds_read_b128 v[108:111], v246 offset:14336
	v_mfma_f32_16x16x32_bf16 v[192:195], v[8:11], v[116:119], v[80:83]
	v_mfma_f32_16x16x32_bf16 v[196:199], v[4:7], v[116:119], v[76:79]
	v_mfma_f32_16x16x32_bf16 v[200:203], v[0:3], v[116:119], v[72:75]
	s_waitcnt lgkmcnt(2)
	v_mfma_f32_16x16x32_bf16 v[204:207], v[12:15], v[136:139], v[68:71]
	v_mfma_f32_16x16x32_bf16 v[208:211], v[8:11], v[136:139], v[64:67]
	v_mfma_f32_16x16x32_bf16 v[212:215], v[4:7], v[136:139], v[60:63]
	v_mfma_f32_16x16x32_bf16 v[216:219], v[0:3], v[136:139], v[56:59]
	s_waitcnt lgkmcnt(1)
	v_mfma_f32_16x16x32_bf16 v[220:223], v[12:15], v[104:107], v[52:55]
	s_nop 2
	v_add_u32_e32 v52, 0x10400, v243
	v_add_u32_e32 v56, 0x10c00, v243
	ds_read_b128 v[52:55], v52
	ds_read_b128 v[84:87], v56
	v_add_u32_e32 v56, 0x11400, v243
	v_add_u32_e32 v57, 0x11c00, v243
	ds_read_b128 v[136:139], v56
	ds_read_b128 v[152:155], v57
	ds_read_b128 v[64:67], v246 offset:1024
	ds_read_b128 v[56:59], v246 offset:3072
	v_mfma_f32_16x16x32_bf16 v[60:63], v[8:11], v[104:107], v[48:51]
	v_mfma_f32_16x16x32_bf16 v[116:119], v[4:7], v[104:107], v[44:47]
	v_mfma_f32_16x16x32_bf16 v[156:159], v[0:3], v[104:107], v[40:43]
	s_waitcnt lgkmcnt(6)
	v_mfma_f32_16x16x32_bf16 v[160:163], v[12:15], v[108:111], v[36:39]
	v_mfma_f32_16x16x32_bf16 v[164:167], v[8:11], v[108:111], v[32:35]
	v_mfma_f32_16x16x32_bf16 v[168:171], v[4:7], v[108:111], v[28:31]
	v_mfma_f32_16x16x32_bf16 v[172:175], v[0:3], v[108:111], v[24:27]
	s_nop 2
	v_cndmask_b32_e64 v24, 0, 1, s[16:17]
	v_cmp_ne_u32_e64 s[0:1], 1, v24
	s_andn2_b64 vcc, exec, s[16:17]
	s_cbranch_vccnz .LBB0_242
	s_mov_b32 m0, s4
	v_lshl_add_u64 v[24:25], s[6:7], 0, v[224:225]
	s_mov_b64 s[8:9], 0x58000
	v_lshl_add_u64 v[28:29], v[24:25], 0, s[8:9]
	s_mov_b64 s[16:17], 0xb0000
	global_load_lds_dwordx4 v[24:25], off
	s_add_i32 m0, s4, 0x2000
	v_lshl_add_u64 v[30:31], v[24:25], 0, s[16:17]
	s_mov_b64 s[18:19], 0x108000
	global_load_lds_dwordx4 v[28:29], off
	s_add_i32 m0, s4, 0x4000
	v_lshl_add_u64 v[32:33], v[24:25], 0, s[18:19]
	global_load_lds_dwordx4 v[30:31], off
	s_add_i32 m0, s4, 0x6000
	v_lshl_add_u64 v[26:27], s[12:13], 0, v[224:225]
	global_load_lds_dwordx4 v[32:33], off
	s_add_i32 m0, s4, 0x8000
	v_lshl_add_u64 v[34:35], v[26:27], 0, s[8:9]
	global_load_lds_dwordx4 v[26:27], off
	s_add_i32 m0, s4, 0xa000
	v_lshl_add_u64 v[36:37], v[26:27], 0, s[16:17]
	global_load_lds_dwordx4 v[34:35], off
	s_add_i32 m0, s4, 0xc000
	v_lshl_add_u64 v[38:39], v[26:27], 0, s[18:19]
	global_load_lds_dwordx4 v[36:37], off
	s_add_i32 m0, s4, 0xe000
	s_nop 0
	global_load_lds_dwordx4 v[38:39], off

; #define WAIT_V(n) asm volatile("s_waitcnt vmcnt(%0)" ::"n"(n) : "memory")
;     ...
;     for (int t = 0; t < nt; ++t) {
;       const int cur = t & 1;
;       const char* sa = shm + cur * STAGE_B;
;       const char* sn = shm + (cur ^ 1) * STAGE_B;
;       const bool more = (t + 1 < nt) || (nitem < ntiles);
; #pragma unroll
;       for (int ks = 0; ks < 2; ++ks) {
; #pragma unroll
;         for (int p = 0; p < NP; ++p) {
;           const int q = ks * NP + p;
;           acc[p * 2][0] = __builtin_amdgcn_mfma_f32_16x16x32_bf16(Bq[BDBL ? ks : 0][0], Aq[q & 1][0], acc[p * 2][0], 0, 0, 0);
;           __builtin_amdgcn_sched_barrier(0);
;           if (q == 2 * NP - 1) {
;             WAIT_V(0);
;             __syncthreads();
;             if (more) {
;               if constexpr (BDBL) {
; #pragma unroll
;                 for (int n = 0; n < 4; ++n) Bq[0][n] = *(const bf16x8*)(sn + boff + (n * 2 + 0) * 1024);
;               }
; #pragma unroll
;               for (int i = 0; i < 2; ++i) Aq[0][i] = *(const bf16x8*)(sn + aoff + (i * 2 + 0) * 1024);
;             }
;           } else if (p + 1 < NP) {
; #pragma unroll
;             for (int i = 0; i < 2; ++i) Aq[(q + 1) & 1][i] = *(const bf16x8*)(sa + aoff + (((p + 1) * 2 + i) * 2 + ks) * 1024);
;           } else {
;             if constexpr (BDBL) {
; #pragma unroll
;               for (int n = 0; n < 4; ++n) Bq[1][n] = *(const bf16x8*)(sa + boff + (n * 2 + 1) * 1024);
;             }
; #pragma unroll
;             for (int i = 0; i < 2; ++i) Aq[(q + 1) & 1][i] = *(const bf16x8*)(sa + aoff + (i * 2 + 1) * 1024);
;           }
;           __builtin_amdgcn_sched_barrier(0);
; #pragma unroll
;           for (int i = 0; i < 2; ++i)
; #pragma unroll
;             for (int n = 0; n < 4; ++n)
;               if (i + n > 0)
;                 acc[p * 2 + i][n] = __builtin_amdgcn_mfma_f32_16x16x32_bf16(Bq[BDBL ? ks : 0][n], Aq[q & 1][i], acc[p * 2 + i][n], 0, 0, 0);
;           __builtin_amdgcn_sched_barrier(0);
;           if (q == GLDS_AT) {
;             if (t + 1 < nt) GLDS_STAGE(cur ^ 1, t + 1, Ab, Bb);
;             else if (nitem < ntiles) GLDS_STAGE(0, 0, nAb, nBb);
;             __builtin_amdgcn_sched_barrier(0);
;           }
.LBB0_459:
	s_waitcnt lgkmcnt(0)
	s_nop 0
	v_mfma_f32_16x16x32_bf16 v[148:151], v[12:15], v[20:23], v[148:151]
	s_and_b32 s14, s22, 0x10000
	s_xor_b32 s15, s14, 0x10000
	v_add_u32_e32 v184, s14, v241
	v_or_b32_e32 v176, s14, v242
	v_bitop3_b32 v185, s22, v242, v233 bitop3:0xce
	v_add_u32_e32 v186, s15, v241
	ds_read_b128 v[156:159], v184 offset:4096
	ds_read_b128 v[160:163], v184 offset:6144
	v_mfma_f32_16x16x32_bf16 v[144:147], v[8:11], v[20:23], v[144:147]
	s_add_i32 s14, s15, s4
	v_lshl_add_u64 v[180:181], v[152:153], 0, s[0:1]
	v_mfma_f32_16x16x32_bf16 v[140:143], v[4:7], v[20:23], v[140:143]
	v_lshl_add_u64 v[182:183], v[180:181], 0, s[38:39]
	s_mov_b32 m0, s14
	v_mfma_f32_16x16x32_bf16 v[20:23], v[0:3], v[20:23], v[136:139]
	s_add_i32 s15, s14, 0x8000
	global_load_lds_dwordx4 v[182:183], off
	v_mfma_f32_16x16x32_bf16 v[132:135], v[12:15], v[16:19], v[132:135]
	v_lshl_add_u64 v[182:183], v[180:181], 0, s[82:83]
	s_add_i32 m0, s14, 0x2000
	v_mfma_f32_16x16x32_bf16 v[128:131], v[8:11], v[16:19], v[128:131]
	global_load_lds_dwordx4 v[182:183], off
	v_lshl_add_u64 v[182:183], v[180:181], 0, s[78:79]
	v_mfma_f32_16x16x32_bf16 v[124:127], v[4:7], v[16:19], v[124:127]
	s_add_i32 m0, s14, 0x4000
	v_lshl_add_u64 v[180:181], v[180:181], 0, s[2:3]
	v_mfma_f32_16x16x32_bf16 v[16:19], v[0:3], v[16:19], v[120:123]
	global_load_lds_dwordx4 v[182:183], off
	s_add_i32 m0, s14, 0x6000
	s_waitcnt lgkmcnt(1)
	v_mfma_f32_16x16x32_bf16 v[116:119], v[12:15], v[156:159], v[116:119]
	s_nop 0
	ds_read_b128 v[120:123], v184 offset:8192
	ds_read_b128 v[136:139], v184 offset:10240
	global_load_lds_dwordx4 v[180:181], off
	v_lshl_add_u64 v[180:181], v[154:155], 0, s[0:1]
	v_mfma_f32_16x16x32_bf16 v[112:115], v[8:11], v[156:159], v[112:115]
	v_lshl_add_u64 v[182:183], v[180:181], 0, s[38:39]
	s_mov_b32 m0, s15
	v_mfma_f32_16x16x32_bf16 v[108:111], v[4:7], v[156:159], v[108:111]
	global_load_lds_dwordx4 v[182:183], off
	v_lshl_add_u64 v[182:183], v[180:181], 0, s[82:83]
	v_mfma_f32_16x16x32_bf16 v[104:107], v[0:3], v[156:159], v[104:107]
	s_add_i32 m0, s14, 0xa000
	s_waitcnt lgkmcnt(2)
	v_mfma_f32_16x16x32_bf16 v[100:103], v[12:15], v[160:163], v[100:103]
	global_load_lds_dwordx4 v[182:183], off
	v_lshl_add_u64 v[182:183], v[180:181], 0, s[78:79]
	v_mfma_f32_16x16x32_bf16 v[96:99], v[8:11], v[160:163], v[96:99]
	s_add_i32 m0, s14, 0xc000
	v_lshl_add_u64 v[180:181], v[180:181], 0, s[2:3]
	v_mfma_f32_16x16x32_bf16 v[92:95], v[4:7], v[160:163], v[92:95]
	global_load_lds_dwordx4 v[182:183], off
	s_add_i32 m0, s14, 0xe000
	v_mfma_f32_16x16x32_bf16 v[88:91], v[0:3], v[160:163], v[88:91]
	global_load_lds_dwordx4 v[180:181], off
	s_waitcnt lgkmcnt(1)
	v_mfma_f32_16x16x32_bf16 v[84:87], v[12:15], v[120:123], v[84:87]
	ds_read_b128 v[156:159], v184 offset:12288
	ds_read_b128 v[160:163], v184 offset:14336
	v_mfma_f32_16x16x32_bf16 v[80:83], v[8:11], v[120:123], v[80:83]
	v_mfma_f32_16x16x32_bf16 v[76:79], v[4:7], v[120:123], v[76:79]
	v_mfma_f32_16x16x32_bf16 v[72:75], v[0:3], v[120:123], v[72:75]
	s_waitcnt lgkmcnt(2)
	v_mfma_f32_16x16x32_bf16 v[68:71], v[12:15], v[136:139], v[68:71]
	v_mfma_f32_16x16x32_bf16 v[64:67], v[8:11], v[136:139], v[64:67]
	v_mfma_f32_16x16x32_bf16 v[60:63], v[4:7], v[136:139], v[60:63]
	v_mfma_f32_16x16x32_bf16 v[56:59], v[0:3], v[136:139], v[56:59]
	s_waitcnt lgkmcnt(1)
	v_mfma_f32_16x16x32_bf16 v[52:55], v[12:15], v[156:159], v[52:55]
	ds_read_b128 v[164:167], v176 offset:33792
	ds_read_b128 v[168:171], v176 offset:35840
	ds_read_b128 v[172:175], v176 offset:37888
	ds_read_b128 v[176:179], v176 offset:39936
	ds_read_b128 v[120:123], v184 offset:1024
	ds_read_b128 v[180:183], v184 offset:3072
	v_mfma_f32_16x16x32_bf16 v[48:51], v[8:11], v[156:159], v[48:51]
	v_mfma_f32_16x16x32_bf16 v[44:47], v[4:7], v[156:159], v[44:47]
	v_mfma_f32_16x16x32_bf16 v[40:43], v[0:3], v[156:159], v[40:43]
	s_waitcnt lgkmcnt(6)
	v_mfma_f32_16x16x32_bf16 v[36:39], v[12:15], v[160:163], v[36:39]
	v_mfma_f32_16x16x32_bf16 v[32:35], v[8:11], v[160:163], v[32:35]
	v_mfma_f32_16x16x32_bf16 v[28:31], v[4:7], v[160:163], v[28:31]
	v_mfma_f32_16x16x32_bf16 v[24:27], v[0:3], v[160:163], v[24:27]
	s_waitcnt lgkmcnt(0)
	v_mfma_f32_16x16x32_bf16 v[148:151], v[164:167], v[120:123], v[148:151]
	ds_read_b128 v[0:3], v184 offset:5120
	ds_read_b128 v[4:7], v184 offset:7168
	v_mfma_f32_16x16x32_bf16 v[144:147], v[168:171], v[120:123], v[144:147]
	v_mfma_f32_16x16x32_bf16 v[140:143], v[172:175], v[120:123], v[140:143]
	v_mfma_f32_16x16x32_bf16 v[136:139], v[176:179], v[120:123], v[20:23]
	v_mfma_f32_16x16x32_bf16 v[132:135], v[164:167], v[180:183], v[132:135]
	v_mfma_f32_16x16x32_bf16 v[128:131], v[168:171], v[180:183], v[128:131]
	v_mfma_f32_16x16x32_bf16 v[124:127], v[172:175], v[180:183], v[124:127]
	v_mfma_f32_16x16x32_bf16 v[120:123], v[176:179], v[180:183], v[16:19]
	s_waitcnt lgkmcnt(1)
	v_mfma_f32_16x16x32_bf16 v[116:119], v[164:167], v[0:3], v[116:119]
	ds_read_b128 v[8:11], v184 offset:9216
	ds_read_b128 v[12:15], v184 offset:11264
	v_mfma_f32_16x16x32_bf16 v[112:115], v[168:171], v[0:3], v[112:115]
	v_mfma_f32_16x16x32_bf16 v[108:111], v[172:175], v[0:3], v[108:111]
	v_mfma_f32_16x16x32_bf16 v[104:107], v[176:179], v[0:3], v[104:107]
	s_waitcnt lgkmcnt(2)
	v_mfma_f32_16x16x32_bf16 v[100:103], v[164:167], v[4:7], v[100:103]
	v_mfma_f32_16x16x32_bf16 v[96:99], v[168:171], v[4:7], v[96:99]
	v_mfma_f32_16x16x32_bf16 v[92:95], v[172:175], v[4:7], v[92:95]
	v_mfma_f32_16x16x32_bf16 v[88:91], v[176:179], v[4:7], v[88:91]
	s_waitcnt lgkmcnt(1)
	v_mfma_f32_16x16x32_bf16 v[84:87], v[164:167], v[8:11], v[84:87]
	ds_read_b128 v[156:159], v184 offset:13312
	ds_read_b128 v[160:163], v184 offset:15360
	v_mfma_f32_16x16x32_bf16 v[80:83], v[168:171], v[8:11], v[80:83]
	v_mfma_f32_16x16x32_bf16 v[76:79], v[172:175], v[8:11], v[76:79]
	v_mfma_f32_16x16x32_bf16 v[72:75], v[176:179], v[8:11], v[72:75]
	s_waitcnt lgkmcnt(2)
	v_mfma_f32_16x16x32_bf16 v[68:71], v[164:167], v[12:15], v[68:71]
	v_mfma_f32_16x16x32_bf16 v[64:67], v[168:171], v[12:15], v[64:67]
	v_mfma_f32_16x16x32_bf16 v[60:63], v[172:175], v[12:15], v[60:63]
	v_mfma_f32_16x16x32_bf16 v[56:59], v[176:179], v[12:15], v[56:59]
	s_waitcnt lgkmcnt(1)
	v_mfma_f32_16x16x32_bf16 v[52:55], v[164:167], v[156:159], v[52:55]
	s_waitcnt vmcnt(0)
	s_waitcnt lgkmcnt(0)
	s_barrier
; #define WAIT_V(n) asm volatile("s_waitcnt vmcnt(%0)" ::"n"(n) : "memory")
;     ...
;     for (int t = 0; t < nt; ++t) {
;       const int cur = t & 1;
;       const char* sa = shm + cur * STAGE_B;
;       const char* sn = shm + (cur ^ 1) * STAGE_B;
;       const bool more = (t + 1 < nt) || (nitem < ntiles);
; #pragma unroll
;       for (int ks = 0; ks < 2; ++ks) {
; #pragma unroll
;         for (int p = 0; p < NP; ++p) {
;           const int q = ks * NP + p;
;           acc[p * 2][0] = __builtin_amdgcn_mfma_f32_16x16x32_bf16(Bq[BDBL ? ks : 0][0], Aq[q & 1][0], acc[p * 2][0], 0, 0, 0);
;           __builtin_amdgcn_sched_barrier(0);
;           if (q == 2 * NP - 1) {
;             WAIT_V(0);
;             __syncthreads();
;             if (more) {
;               if constexpr (BDBL) {
; #pragma unroll
;                 for (int n = 0; n < 4; ++n) Bq[0][n] = *(const bf16x8*)(sn + boff + (n * 2 + 0) * 1024);
;               }
; #pragma unroll
;               for (int i = 0; i < 2; ++i) Aq[0][i] = *(const bf16x8*)(sn + aoff + (i * 2 + 0) * 1024);
;             }
;           } else if (p + 1 < NP) {
; #pragma unroll
;             for (int i = 0; i < 2; ++i) Aq[(q + 1) & 1][i] = *(const bf16x8*)(sa + aoff + (((p + 1) * 2 + i) * 2 + ks) * 1024);
;           } else {
;             if constexpr (BDBL) {
; #pragma unroll
;               for (int n = 0; n < 4; ++n) Bq[1][n] = *(const bf16x8*)(sa + boff + (n * 2 + 1) * 1024);
;             }
; #pragma unroll
;             for (int i = 0; i < 2; ++i) Aq[(q + 1) & 1][i] = *(const bf16x8*)(sa + aoff + (i * 2 + 1) * 1024);
;           }
;           __builtin_amdgcn_sched_barrier(0);
; #pragma unroll
;           for (int i = 0; i < 2; ++i)
; #pragma unroll
;             for (int n = 0; n < 4; ++n)
;               if (i + n > 0)
;                 acc[p * 2 + i][n] = __builtin_amdgcn_mfma_f32_16x16x32_bf16(Bq[BDBL ? ks : 0][n], Aq[q & 1][i], acc[p * 2 + i][n], 0, 0, 0);
;           __builtin_amdgcn_sched_barrier(0);
;           if (q == GLDS_AT) {
;             if (t + 1 < nt) GLDS_STAGE(cur ^ 1, t + 1, Ab, Bb);
;             else if (nitem < ntiles) GLDS_STAGE(0, 0, nAb, nBb);
;             __builtin_amdgcn_sched_barrier(0);
;           }
	ds_read_b128 v[12:15], v185 offset:32768
	ds_read_b128 v[8:11], v185 offset:34816
	ds_read_b128 v[4:7], v185 offset:36864
	ds_read_b128 v[0:3], v185 offset:38912
	ds_read_b128 v[20:23], v186
	ds_read_b128 v[16:19], v186 offset:2048
	v_mfma_f32_16x16x32_bf16 v[48:51], v[168:171], v[156:159], v[48:51]
	v_mfma_f32_16x16x32_bf16 v[44:47], v[172:175], v[156:159], v[44:47]
	v_mfma_f32_16x16x32_bf16 v[40:43], v[176:179], v[156:159], v[40:43]
	v_mfma_f32_16x16x32_bf16 v[36:39], v[164:167], v[160:163], v[36:39]
	v_mfma_f32_16x16x32_bf16 v[32:35], v[168:171], v[160:163], v[32:35]
	v_mfma_f32_16x16x32_bf16 v[28:31], v[172:175], v[160:163], v[28:31]
	v_mfma_f32_16x16x32_bf16 v[24:27], v[176:179], v[160:163], v[24:27]
	s_add_u32 s0, s0, 0x80
	s_addc_u32 s1, s1, 0
	s_add_i32 s22, s22, 0x10000
	s_cmpk_eq_i32 s0, 0x780
	s_cbranch_scc0 .LBB0_459
	s_waitcnt lgkmcnt(1)
	v_mfma_f32_16x16x32_bf16 v[148:151], v[12:15], v[20:23], v[148:151]
	v_add_u32_e32 v246, 0x10000, v241
	ds_read_b128 v[152:155], v246 offset:4096
	ds_read_b128 v[156:159], v246 offset:6144
	v_mfma_f32_16x16x32_bf16 v[144:147], v[8:11], v[20:23], v[144:147]
	v_mfma_f32_16x16x32_bf16 v[140:143], v[4:7], v[20:23], v[140:143]
	v_mfma_f32_16x16x32_bf16 v[20:23], v[0:3], v[20:23], v[136:139]
	s_waitcnt lgkmcnt(2)
	v_mfma_f32_16x16x32_bf16 v[136:139], v[12:15], v[16:19], v[132:135]
	v_mfma_f32_16x16x32_bf16 v[128:131], v[8:11], v[16:19], v[128:131]
	v_mfma_f32_16x16x32_bf16 v[124:127], v[4:7], v[16:19], v[124:127]
	v_mfma_f32_16x16x32_bf16 v[16:19], v[0:3], v[16:19], v[120:123]
	s_waitcnt lgkmcnt(1)
	v_mfma_f32_16x16x32_bf16 v[176:179], v[12:15], v[152:155], v[116:119]
	s_nop 2
	ds_read_b128 v[116:119], v246 offset:8192
	ds_read_b128 v[120:123], v246 offset:10240
	v_mfma_f32_16x16x32_bf16 v[180:183], v[8:11], v[152:155], v[112:115]
	v_mfma_f32_16x16x32_bf16 v[184:187], v[4:7], v[152:155], v[108:111]
	v_mfma_f32_16x16x32_bf16 v[188:191], v[0:3], v[152:155], v[104:107]
	s_waitcnt lgkmcnt(2)
	v_mfma_f32_16x16x32_bf16 v[100:103], v[12:15], v[156:159], v[100:103]
	v_mfma_f32_16x16x32_bf16 v[96:99], v[8:11], v[156:159], v[96:99]
	v_mfma_f32_16x16x32_bf16 v[92:95], v[4:7], v[156:159], v[92:95]
	v_mfma_f32_16x16x32_bf16 v[88:91], v[0:3], v[156:159], v[88:91]
	s_waitcnt lgkmcnt(1)
	v_mfma_f32_16x16x32_bf16 v[192:195], v[12:15], v[116:119], v[84:87]
	s_nop 2
	ds_read_b128 v[84:87], v246 offset:12288
	ds_read_b128 v[104:107], v246 offset:14336
	v_mfma_f32_16x16x32_bf16 v[196:199], v[8:11], v[116:119], v[80:83]
	v_mfma_f32_16x16x32_bf16 v[200:203], v[4:7], v[116:119], v[76:79]
	v_mfma_f32_16x16x32_bf16 v[204:207], v[0:3], v[116:119], v[72:75]
	s_waitcnt lgkmcnt(2)
	v_mfma_f32_16x16x32_bf16 v[208:211], v[12:15], v[120:123], v[68:71]
	v_mfma_f32_16x16x32_bf16 v[212:215], v[8:11], v[120:123], v[64:67]
	v_mfma_f32_16x16x32_bf16 v[216:219], v[4:7], v[120:123], v[60:63]
	v_mfma_f32_16x16x32_bf16 v[56:59], v[0:3], v[120:123], v[56:59]
	s_waitcnt lgkmcnt(1)
	v_mfma_f32_16x16x32_bf16 v[220:223], v[12:15], v[84:87], v[52:55]
	s_nop 2
	v_add_u32_e32 v52, 0x10400, v243
	v_add_u32_e32 v60, 0x10c00, v243
	v_add_u32_e32 v64, 0x11400, v243
	v_add_u32_e32 v65, 0x11c00, v243
	ds_read_b128 v[52:55], v52
	ds_read_b128 v[60:63], v60
	ds_read_b128 v[120:123], v64
	ds_read_b128 v[132:135], v65
	ds_read_b128 v[72:75], v246 offset:1024
	ds_read_b128 v[64:67], v246 offset:3072
	v_mfma_f32_16x16x32_bf16 v[68:71], v[8:11], v[84:87], v[48:51]
	v_mfma_f32_16x16x32_bf16 v[116:119], v[4:7], v[84:87], v[44:47]
	v_mfma_f32_16x16x32_bf16 v[152:155], v[0:3], v[84:87], v[40:43]
	s_waitcnt lgkmcnt(6)
	v_mfma_f32_16x16x32_bf16 v[156:159], v[12:15], v[104:107], v[36:39]
	v_mfma_f32_16x16x32_bf16 v[160:163], v[8:11], v[104:107], v[32:35]
	v_mfma_f32_16x16x32_bf16 v[164:167], v[4:7], v[104:107], v[28:31]
	v_mfma_f32_16x16x32_bf16 v[168:171], v[0:3], v[104:107], v[24:27]
	s_nop 2
	v_cndmask_b32_e64 v24, 0, 1, s[12:13]
	v_cmp_ne_u32_e64 s[0:1], 1, v24
	s_andn2_b64 vcc, exec, s[12:13]
	s_cbranch_vccnz .LBB0_462
	s_mov_b32 m0, s4
	v_lshl_add_u64 v[24:25], s[6:7], 0, v[224:225]
	v_lshl_add_u64 v[28:29], v[24:25], 0, s[76:77]
	global_load_lds_dwordx4 v[24:25], off
	s_add_i32 m0, s4, 0x2000
	v_lshl_add_u64 v[30:31], v[24:25], 0, s[96:97]
	global_load_lds_dwordx4 v[28:29], off
	s_add_i32 m0, s4, 0x4000
	v_lshl_add_u64 v[32:33], v[24:25], 0, s[70:71]
	global_load_lds_dwordx4 v[30:31], off
	s_add_i32 m0, s4, 0x6000
	v_lshl_add_u64 v[26:27], s[8:9], 0, v[224:225]
	global_load_lds_dwordx4 v[32:33], off
	s_add_i32 m0, s4, 0x8000
	v_lshl_add_u64 v[34:35], v[26:27], 0, s[76:77]
	global_load_lds_dwordx4 v[26:27], off
	s_add_i32 m0, s4, 0xa000
	v_lshl_add_u64 v[36:37], v[26:27], 0, s[96:97]
	global_load_lds_dwordx4 v[34:35], off
	s_add_i32 m0, s4, 0xc000
	v_lshl_add_u64 v[38:39], v[26:27], 0, s[70:71]
	global_load_lds_dwordx4 v[36:37], off
	s_add_i32 m0, s4, 0xe000
	s_nop 0
	global_load_lds_dwordx4 v[38:39], off

;     ...
;     for (int t = 0; t < nt; ++t) {
;       const int cur = t & 1;
;       const char* sa = shm + cur * STAGE_B;
;       const char* sn = shm + (cur ^ 1) * STAGE_B;
;       const bool more = (t + 1 < nt) || (nitem < ntiles);
; #pragma unroll
;       for (int ks = 0; ks < 2; ++ks) {
; #pragma unroll
;         for (int p = 0; p < NP; ++p) {
;           const int q = ks * NP + p;
;           acc[p * 2][0] = __builtin_amdgcn_mfma_f32_16x16x32_bf16(Bq[BDBL ? ks : 0][0], Aq[q & 1][0], acc[p * 2][0], 0, 0, 0);
;           __builtin_amdgcn_sched_barrier(0);
;           if (q == 2 * NP - 1) {
;             WAIT_V(0);
;             __syncthreads();
;             if (more) {
;               if constexpr (BDBL) {
; #pragma unroll
;                 for (int n = 0; n < 4; ++n) Bq[0][n] = *(const bf16x8*)(sn + boff + (n * 2 + 0) * 1024);
;               }
; #pragma unroll
;               for (int i = 0; i < 2; ++i) Aq[0][i] = *(const bf16x8*)(sn + aoff + (i * 2 + 0) * 1024);
;             }
;           } else if (p + 1 < NP) {
; #pragma unroll
;             for (int i = 0; i < 2; ++i) Aq[(q + 1) & 1][i] = *(const bf16x8*)(sa + aoff + (((p + 1) * 2 + i) * 2 + ks) * 1024);
;           } else {
;             if constexpr (BDBL) {
; #pragma unroll
;               for (int n = 0; n < 4; ++n) Bq[1][n] = *(const bf16x8*)(sa + boff + (n * 2 + 1) * 1024);
;             }
; #pragma unroll
;             for (int i = 0; i < 2; ++i) Aq[(q + 1) & 1][i] = *(const bf16x8*)(sa + aoff + (i * 2 + 1) * 1024);
;           }
;           __builtin_amdgcn_sched_barrier(0);
; #pragma unroll
;           for (int i = 0; i < 2; ++i)
; #pragma unroll
;             for (int n = 0; n < 4; ++n)
;               if (i + n > 0)
;                 acc[p * 2 + i][n] = __builtin_amdgcn_mfma_f32_16x16x32_bf16(Bq[BDBL ? ks : 0][n], Aq[q & 1][i], acc[p * 2 + i][n], 0, 0, 0);
;           __builtin_amdgcn_sched_barrier(0);
;           if (q == GLDS_AT) {
;             if (t + 1 < nt) GLDS_STAGE(cur ^ 1, t + 1, Ab, Bb);
;             else if (nitem < ntiles) GLDS_STAGE(0, 0, nAb, nBb);
;             __builtin_amdgcn_sched_barrier(0);
;           }
;           if constexpr (!BDBL) {
;             if (p + 1 == NP) {
;               if (ks == 0) {
; #pragma unroll
;                 for (int n = 0; n < 4; ++n) Bq[0][n] = *(const bf16x8*)(sa + boff + (n * 2 + 1) * 1024);
;               } else if (more) {
.LBB0_742:
	s_waitcnt lgkmcnt(0)
	s_nop 0
	v_mfma_f32_16x16x32_bf16 v[148:151], v[4:7], v[20:23], v[148:151]
	s_and_b32 s14, s22, 0x10000
	s_xor_b32 s15, s14, 0x10000
	v_add_u32_e32 v168, s14, v222
	v_add_u32_e32 v169, s15, v222
	v_bitop3_b32 v170, s22, v223, v233 bitop3:0xce
	v_or_b32_e32 v171, s14, v223
	ds_read_b128 v[156:159], v168 offset:4096
	ds_read_b128 v[160:163], v168 offset:6144
	v_mfma_f32_16x16x32_bf16 v[144:147], v[0:3], v[20:23], v[144:147]
	s_add_i32 s14, s15, s4
	v_lshl_add_u64 v[164:165], v[152:153], 0, s[0:1]
	v_mfma_f32_16x16x32_bf16 v[140:143], v[12:15], v[20:23], v[140:143]
	v_lshl_add_u64 v[166:167], v[164:165], 0, s[38:39]
	s_mov_b32 m0, s14
	v_mfma_f32_16x16x32_bf16 v[20:23], v[8:11], v[20:23], v[136:139]
	s_add_i32 s15, s14, 0x8000
	global_load_lds_dwordx4 v[166:167], off
	v_mfma_f32_16x16x32_bf16 v[132:135], v[4:7], v[16:19], v[132:135]
	v_lshl_add_u64 v[166:167], v[164:165], 0, s[82:83]
	s_add_i32 m0, s14, 0x2000
	v_mfma_f32_16x16x32_bf16 v[128:131], v[0:3], v[16:19], v[128:131]
	global_load_lds_dwordx4 v[166:167], off
	v_lshl_add_u64 v[166:167], v[164:165], 0, s[78:79]
	v_mfma_f32_16x16x32_bf16 v[124:127], v[12:15], v[16:19], v[124:127]
	s_add_i32 m0, s14, 0x4000
	v_lshl_add_u64 v[164:165], v[164:165], 0, s[2:3]
	v_mfma_f32_16x16x32_bf16 v[16:19], v[8:11], v[16:19], v[120:123]
	global_load_lds_dwordx4 v[166:167], off
	s_add_i32 m0, s14, 0x6000
	s_waitcnt lgkmcnt(1)
	v_mfma_f32_16x16x32_bf16 v[116:119], v[4:7], v[156:159], v[116:119]
	s_nop 0
	ds_read_b128 v[120:123], v168 offset:8192
	ds_read_b128 v[136:139], v168 offset:10240
	global_load_lds_dwordx4 v[164:165], off
	v_lshl_add_u64 v[164:165], v[154:155], 0, s[0:1]
	v_mfma_f32_16x16x32_bf16 v[112:115], v[0:3], v[156:159], v[112:115]
	v_lshl_add_u64 v[166:167], v[164:165], 0, s[38:39]
	s_mov_b32 m0, s15
	v_mfma_f32_16x16x32_bf16 v[108:111], v[12:15], v[156:159], v[108:111]
	global_load_lds_dwordx4 v[166:167], off
	v_lshl_add_u64 v[166:167], v[164:165], 0, s[82:83]
	v_mfma_f32_16x16x32_bf16 v[104:107], v[8:11], v[156:159], v[104:107]
	s_add_i32 m0, s14, 0xa000
	s_waitcnt lgkmcnt(2)
	v_mfma_f32_16x16x32_bf16 v[100:103], v[4:7], v[160:163], v[100:103]
	global_load_lds_dwordx4 v[166:167], off
	v_lshl_add_u64 v[166:167], v[164:165], 0, s[78:79]
	v_mfma_f32_16x16x32_bf16 v[96:99], v[0:3], v[160:163], v[96:99]
	s_add_i32 m0, s14, 0xc000
	v_lshl_add_u64 v[164:165], v[164:165], 0, s[2:3]
	v_mfma_f32_16x16x32_bf16 v[92:95], v[12:15], v[160:163], v[92:95]
	global_load_lds_dwordx4 v[166:167], off
	s_add_i32 m0, s14, 0xe000
	v_mfma_f32_16x16x32_bf16 v[88:91], v[8:11], v[160:163], v[88:91]
	global_load_lds_dwordx4 v[164:165], off
	s_waitcnt lgkmcnt(1)
	v_mfma_f32_16x16x32_bf16 v[84:87], v[4:7], v[120:123], v[84:87]
	ds_read_b128 v[156:159], v168 offset:12288
	ds_read_b128 v[160:163], v168 offset:14336
	v_mfma_f32_16x16x32_bf16 v[80:83], v[0:3], v[120:123], v[80:83]
	v_mfma_f32_16x16x32_bf16 v[76:79], v[12:15], v[120:123], v[76:79]
	v_mfma_f32_16x16x32_bf16 v[72:75], v[8:11], v[120:123], v[72:75]
	s_waitcnt lgkmcnt(2)
	v_mfma_f32_16x16x32_bf16 v[68:71], v[4:7], v[136:139], v[68:71]
	v_mfma_f32_16x16x32_bf16 v[64:67], v[0:3], v[136:139], v[64:67]
	v_mfma_f32_16x16x32_bf16 v[60:63], v[12:15], v[136:139], v[60:63]
	v_mfma_f32_16x16x32_bf16 v[56:59], v[8:11], v[136:139], v[56:59]
	s_waitcnt lgkmcnt(1)
	v_mfma_f32_16x16x32_bf16 v[52:55], v[4:7], v[156:159], v[52:55]
	ds_read_b128 v[120:123], v168 offset:1024
	ds_read_b128 v[164:167], v168 offset:3072
	v_mfma_f32_16x16x32_bf16 v[48:51], v[0:3], v[156:159], v[48:51]
	v_mfma_f32_16x16x32_bf16 v[44:47], v[12:15], v[156:159], v[44:47]
	v_mfma_f32_16x16x32_bf16 v[40:43], v[8:11], v[156:159], v[40:43]
	s_waitcnt lgkmcnt(2)
	v_mfma_f32_16x16x32_bf16 v[4:7], v[4:7], v[160:163], v[36:39]
	v_mfma_f32_16x16x32_bf16 v[0:3], v[0:3], v[160:163], v[32:35]
	v_mfma_f32_16x16x32_bf16 v[12:15], v[12:15], v[160:163], v[28:31]
	v_mfma_f32_16x16x32_bf16 v[8:11], v[8:11], v[160:163], v[24:27]
	ds_read_b128 v[24:27], v171 offset:33792
	ds_read_b128 v[28:31], v171 offset:35840
	ds_read_b128 v[156:159], v171 offset:37888
	ds_read_b128 v[160:163], v171 offset:39936
	s_waitcnt lgkmcnt(0)
	v_mfma_f32_16x16x32_bf16 v[148:151], v[24:27], v[120:123], v[148:151]
	ds_read_b128 v[32:35], v168 offset:5120
	ds_read_b128 v[36:39], v168 offset:7168
	v_mfma_f32_16x16x32_bf16 v[144:147], v[28:31], v[120:123], v[144:147]
	v_mfma_f32_16x16x32_bf16 v[140:143], v[156:159], v[120:123], v[140:143]
	v_mfma_f32_16x16x32_bf16 v[136:139], v[160:163], v[120:123], v[20:23]
	v_mfma_f32_16x16x32_bf16 v[132:135], v[24:27], v[164:167], v[132:135]
	v_mfma_f32_16x16x32_bf16 v[128:131], v[28:31], v[164:167], v[128:131]
	v_mfma_f32_16x16x32_bf16 v[124:127], v[156:159], v[164:167], v[124:127]
	v_mfma_f32_16x16x32_bf16 v[120:123], v[160:163], v[164:167], v[16:19]
	s_waitcnt lgkmcnt(1)
	v_mfma_f32_16x16x32_bf16 v[116:119], v[24:27], v[32:35], v[116:119]
	s_nop 0
	ds_read_b128 v[16:19], v168 offset:9216
	ds_read_b128 v[20:23], v168 offset:11264
	v_mfma_f32_16x16x32_bf16 v[112:115], v[28:31], v[32:35], v[112:115]
	v_mfma_f32_16x16x32_bf16 v[108:111], v[156:159], v[32:35], v[108:111]
	v_mfma_f32_16x16x32_bf16 v[104:107], v[160:163], v[32:35], v[104:107]
	s_waitcnt lgkmcnt(2)
	v_mfma_f32_16x16x32_bf16 v[100:103], v[24:27], v[36:39], v[100:103]
	v_mfma_f32_16x16x32_bf16 v[96:99], v[28:31], v[36:39], v[96:99]
	v_mfma_f32_16x16x32_bf16 v[92:95], v[156:159], v[36:39], v[92:95]
	v_mfma_f32_16x16x32_bf16 v[88:91], v[160:163], v[36:39], v[88:91]
	s_waitcnt lgkmcnt(1)
	v_mfma_f32_16x16x32_bf16 v[84:87], v[24:27], v[16:19], v[84:87]
	ds_read_b128 v[32:35], v168 offset:13312
	ds_read_b128 v[164:167], v168 offset:15360
	v_mfma_f32_16x16x32_bf16 v[80:83], v[28:31], v[16:19], v[80:83]
	v_mfma_f32_16x16x32_bf16 v[76:79], v[156:159], v[16:19], v[76:79]
	v_mfma_f32_16x16x32_bf16 v[72:75], v[160:163], v[16:19], v[72:75]
	s_waitcnt lgkmcnt(2)
	v_mfma_f32_16x16x32_bf16 v[68:71], v[24:27], v[20:23], v[68:71]
	v_mfma_f32_16x16x32_bf16 v[64:67], v[28:31], v[20:23], v[64:67]
	v_mfma_f32_16x16x32_bf16 v[60:63], v[156:159], v[20:23], v[60:63]
	v_mfma_f32_16x16x32_bf16 v[56:59], v[160:163], v[20:23], v[56:59]
	s_waitcnt lgkmcnt(1)
	v_mfma_f32_16x16x32_bf16 v[52:55], v[24:27], v[32:35], v[52:55]
	s_waitcnt vmcnt(0)
	s_waitcnt lgkmcnt(0)
	s_barrier
;     ...
;     for (int t = 0; t < nt; ++t) {
;       const int cur = t & 1;
;       const char* sa = shm + cur * STAGE_B;
;       const char* sn = shm + (cur ^ 1) * STAGE_B;
;       const bool more = (t + 1 < nt) || (nitem < ntiles);
; #pragma unroll
;       for (int ks = 0; ks < 2; ++ks) {
; #pragma unroll
;         for (int p = 0; p < NP; ++p) {
;           const int q = ks * NP + p;
;           acc[p * 2][0] = __builtin_amdgcn_mfma_f32_16x16x32_bf16(Bq[BDBL ? ks : 0][0], Aq[q & 1][0], acc[p * 2][0], 0, 0, 0);
;           __builtin_amdgcn_sched_barrier(0);
;           if (q == 2 * NP - 1) {
;             WAIT_V(0);
;             __syncthreads();
;             if (more) {
;               if constexpr (BDBL) {
; #pragma unroll
;                 for (int n = 0; n < 4; ++n) Bq[0][n] = *(const bf16x8*)(sn + boff + (n * 2 + 0) * 1024);
;               }
; #pragma unroll
;               for (int i = 0; i < 2; ++i) Aq[0][i] = *(const bf16x8*)(sn + aoff + (i * 2 + 0) * 1024);
;             }
;           } else if (p + 1 < NP) {
; #pragma unroll
;             for (int i = 0; i < 2; ++i) Aq[(q + 1) & 1][i] = *(const bf16x8*)(sa + aoff + (((p + 1) * 2 + i) * 2 + ks) * 1024);
;           } else {
;             if constexpr (BDBL) {
; #pragma unroll
;               for (int n = 0; n < 4; ++n) Bq[1][n] = *(const bf16x8*)(sa + boff + (n * 2 + 1) * 1024);
;             }
; #pragma unroll
;             for (int i = 0; i < 2; ++i) Aq[(q + 1) & 1][i] = *(const bf16x8*)(sa + aoff + (i * 2 + 1) * 1024);
;           }
;           __builtin_amdgcn_sched_barrier(0);
; #pragma unroll
;           for (int i = 0; i < 2; ++i)
; #pragma unroll
;             for (int n = 0; n < 4; ++n)
;               if (i + n > 0)
;                 acc[p * 2 + i][n] = __builtin_amdgcn_mfma_f32_16x16x32_bf16(Bq[BDBL ? ks : 0][n], Aq[q & 1][i], acc[p * 2 + i][n], 0, 0, 0);
;           __builtin_amdgcn_sched_barrier(0);
;           if (q == GLDS_AT) {
;             if (t + 1 < nt) GLDS_STAGE(cur ^ 1, t + 1, Ab, Bb);
;             else if (nitem < ntiles) GLDS_STAGE(0, 0, nAb, nBb);
;             __builtin_amdgcn_sched_barrier(0);
;           }
;           if constexpr (!BDBL) {
;             if (p + 1 == NP) {
;               if (ks == 0) {
; #pragma unroll
;                 for (int n = 0; n < 4; ++n) Bq[0][n] = *(const bf16x8*)(sa + boff + (n * 2 + 1) * 1024);
;               } else if (more) {
	ds_read_b128 v[20:23], v169
	ds_read_b128 v[16:19], v169 offset:2048
	v_mfma_f32_16x16x32_bf16 v[48:51], v[28:31], v[32:35], v[48:51]
	v_mfma_f32_16x16x32_bf16 v[44:47], v[156:159], v[32:35], v[44:47]
	v_mfma_f32_16x16x32_bf16 v[40:43], v[160:163], v[32:35], v[40:43]
	v_mfma_f32_16x16x32_bf16 v[36:39], v[24:27], v[164:167], v[4:7]
	v_mfma_f32_16x16x32_bf16 v[32:35], v[28:31], v[164:167], v[0:3]
	v_mfma_f32_16x16x32_bf16 v[28:31], v[156:159], v[164:167], v[12:15]
	v_mfma_f32_16x16x32_bf16 v[24:27], v[160:163], v[164:167], v[8:11]
	ds_read_b128 v[4:7], v170 offset:32768
	ds_read_b128 v[0:3], v170 offset:34816
	ds_read_b128 v[12:15], v170 offset:36864
	ds_read_b128 v[8:11], v170 offset:38912
	s_add_u32 s0, s0, 0x80
	s_addc_u32 s1, s1, 0
	s_add_i32 s22, s22, 0x10000
	s_cmpk_eq_i32 s0, 0x780
	s_cbranch_scc0 .LBB0_742
	s_waitcnt lgkmcnt(3)
	v_mfma_f32_16x16x32_bf16 v[148:151], v[4:7], v[20:23], v[148:151]
	v_add_u32_e32 v224, 0x10000, v222
	ds_read_b128 v[152:155], v224 offset:4096
	ds_read_b128 v[156:159], v224 offset:6144
	s_waitcnt lgkmcnt(4)
	v_mfma_f32_16x16x32_bf16 v[164:167], v[0:3], v[20:23], v[144:147]
	s_waitcnt lgkmcnt(3)
	v_mfma_f32_16x16x32_bf16 v[140:143], v[12:15], v[20:23], v[140:143]
	s_waitcnt lgkmcnt(2)
	v_mfma_f32_16x16x32_bf16 v[20:23], v[8:11], v[20:23], v[136:139]
	v_mfma_f32_16x16x32_bf16 v[132:135], v[4:7], v[16:19], v[132:135]
	v_mfma_f32_16x16x32_bf16 v[168:171], v[0:3], v[16:19], v[128:131]
	v_mfma_f32_16x16x32_bf16 v[124:127], v[12:15], v[16:19], v[124:127]
	v_mfma_f32_16x16x32_bf16 v[16:19], v[8:11], v[16:19], v[120:123]
	s_waitcnt lgkmcnt(1)
	v_mfma_f32_16x16x32_bf16 v[116:119], v[4:7], v[152:155], v[116:119]
	s_nop 0
	ds_read_b128 v[120:123], v224 offset:8192
	ds_read_b128 v[128:131], v224 offset:10240
	v_mfma_f32_16x16x32_bf16 v[172:175], v[0:3], v[152:155], v[112:115]
	v_mfma_f32_16x16x32_bf16 v[108:111], v[12:15], v[152:155], v[108:111]
	v_mfma_f32_16x16x32_bf16 v[176:179], v[8:11], v[152:155], v[104:107]
	s_waitcnt lgkmcnt(2)
	v_mfma_f32_16x16x32_bf16 v[100:103], v[4:7], v[156:159], v[100:103]
	v_mfma_f32_16x16x32_bf16 v[180:183], v[0:3], v[156:159], v[96:99]
	v_mfma_f32_16x16x32_bf16 v[92:95], v[12:15], v[156:159], v[92:95]
	v_mfma_f32_16x16x32_bf16 v[184:187], v[8:11], v[156:159], v[88:91]
	s_waitcnt lgkmcnt(1)
	v_mfma_f32_16x16x32_bf16 v[84:87], v[4:7], v[120:123], v[84:87]
	s_nop 0
	ds_read_b128 v[88:91], v224 offset:12288
	ds_read_b128 v[96:99], v224 offset:14336
	v_mfma_f32_16x16x32_bf16 v[188:191], v[0:3], v[120:123], v[80:83]
	v_mfma_f32_16x16x32_bf16 v[76:79], v[12:15], v[120:123], v[76:79]
	v_mfma_f32_16x16x32_bf16 v[192:195], v[8:11], v[120:123], v[72:75]
	s_waitcnt lgkmcnt(2)
	v_mfma_f32_16x16x32_bf16 v[68:71], v[4:7], v[128:131], v[68:71]
	v_mfma_f32_16x16x32_bf16 v[196:199], v[0:3], v[128:131], v[64:67]
	v_mfma_f32_16x16x32_bf16 v[60:63], v[12:15], v[128:131], v[60:63]
	v_mfma_f32_16x16x32_bf16 v[200:203], v[8:11], v[128:131], v[56:59]
	s_waitcnt lgkmcnt(1)
	v_mfma_f32_16x16x32_bf16 v[204:207], v[4:7], v[88:91], v[52:55]
	ds_read_b128 v[64:67], v224 offset:1024
	ds_read_b128 v[56:59], v224 offset:3072
	v_mfma_f32_16x16x32_bf16 v[52:55], v[0:3], v[88:91], v[48:51]
	v_mfma_f32_16x16x32_bf16 v[44:47], v[12:15], v[88:91], v[44:47]
	v_mfma_f32_16x16x32_bf16 v[152:155], v[8:11], v[88:91], v[40:43]
	s_waitcnt lgkmcnt(2)
	v_mfma_f32_16x16x32_bf16 v[36:39], v[4:7], v[96:99], v[36:39]
	v_mfma_f32_16x16x32_bf16 v[156:159], v[0:3], v[96:99], v[32:35]
	v_mfma_f32_16x16x32_bf16 v[28:31], v[12:15], v[96:99], v[28:31]
	v_mfma_f32_16x16x32_bf16 v[160:163], v[8:11], v[96:99], v[24:27]
	v_cndmask_b32_e64 v0, 0, 1, s[6:7]
	v_cmp_ne_u32_e64 s[0:1], 1, v0
	s_andn2_b64 vcc, exec, s[6:7]
	s_cbranch_vccnz .LBB0_745
	s_mov_b32 m0, s4
	v_lshl_add_u64 v[0:1], s[8:9], 0, v[208:209]
	v_lshl_add_u64 v[4:5], v[0:1], 0, s[76:77]
	global_load_lds_dwordx4 v[0:1], off
	s_add_i32 m0, s4, 0x2000
	v_lshl_add_u64 v[6:7], v[0:1], 0, s[96:97]
	global_load_lds_dwordx4 v[4:5], off
	s_add_i32 m0, s4, 0x4000
	v_lshl_add_u64 v[8:9], v[0:1], 0, s[70:71]
	global_load_lds_dwordx4 v[6:7], off
	s_add_i32 m0, s4, 0x6000
	v_lshl_add_u64 v[2:3], s[10:11], 0, v[208:209]
	global_load_lds_dwordx4 v[8:9], off
	s_add_i32 m0, s4, 0x8000
	v_lshl_add_u64 v[10:11], v[2:3], 0, s[76:77]
	global_load_lds_dwordx4 v[2:3], off
	s_add_i32 m0, s4, 0xa000
	v_lshl_add_u64 v[12:13], v[2:3], 0, s[96:97]
	global_load_lds_dwordx4 v[10:11], off
	s_add_i32 m0, s4, 0xc000
	v_lshl_add_u64 v[14:15], v[2:3], 0, s[70:71]
	global_load_lds_dwordx4 v[12:13], off
	s_add_i32 m0, s4, 0xe000
	s_nop 0
	global_load_lds_dwordx4 v[14:15], off

; #define WAIT_V(n) asm volatile("s_waitcnt vmcnt(%0)" ::"n"(n) : "memory")
;     ...
;     for (int t = 0; t < nt; ++t) {
;       const int cur = t & 1;
;       const char* sa = shm + cur * STAGE_B;
;       const char* sn = shm + (cur ^ 1) * STAGE_B;
;       const bool more = (t + 1 < nt) || (nitem < ntiles);
; #pragma unroll
;       for (int ks = 0; ks < 2; ++ks) {
; #pragma unroll
;         for (int p = 0; p < NP; ++p) {
;           const int q = ks * NP + p;
;           acc[p * 2][0] = __builtin_amdgcn_mfma_f32_16x16x32_bf16(Bq[BDBL ? ks : 0][0], Aq[q & 1][0], acc[p * 2][0], 0, 0, 0);
;           __builtin_amdgcn_sched_barrier(0);
;           if (q == 2 * NP - 1) {
;             WAIT_V(0);
;             __syncthreads();
;             if (more) {
;               if constexpr (BDBL) {
; #pragma unroll
;                 for (int n = 0; n < 4; ++n) Bq[0][n] = *(const bf16x8*)(sn + boff + (n * 2 + 0) * 1024);
;               }
; #pragma unroll
;               for (int i = 0; i < 2; ++i) Aq[0][i] = *(const bf16x8*)(sn + aoff + (i * 2 + 0) * 1024);
;             }
;           } else if (p + 1 < NP) {
; #pragma unroll
;             for (int i = 0; i < 2; ++i) Aq[(q + 1) & 1][i] = *(const bf16x8*)(sa + aoff + (((p + 1) * 2 + i) * 2 + ks) * 1024);
;           } else {
;             if constexpr (BDBL) {
; #pragma unroll
;               for (int n = 0; n < 4; ++n) Bq[1][n] = *(const bf16x8*)(sa + boff + (n * 2 + 1) * 1024);
;             }
; #pragma unroll
;             for (int i = 0; i < 2; ++i) Aq[(q + 1) & 1][i] = *(const bf16x8*)(sa + aoff + (i * 2 + 1) * 1024);
;           }
;           __builtin_amdgcn_sched_barrier(0);
; #pragma unroll
;           for (int i = 0; i < 2; ++i)
; #pragma unroll
;             for (int n = 0; n < 4; ++n)
;               if (i + n > 0)
;                 acc[p * 2 + i][n] = __builtin_amdgcn_mfma_f32_16x16x32_bf16(Bq[BDBL ? ks : 0][n], Aq[q & 1][i], acc[p * 2 + i][n], 0, 0, 0);
;           __builtin_amdgcn_sched_barrier(0);
;           if (q == GLDS_AT) {
;             if (t + 1 < nt) GLDS_STAGE(cur ^ 1, t + 1, Ab, Bb);
;             else if (nitem < ntiles) GLDS_STAGE(0, 0, nAb, nBb);
;             __builtin_amdgcn_sched_barrier(0);
;           }
.LBB0_1058:
	s_waitcnt lgkmcnt(0)
	s_nop 0
	v_mfma_f32_16x16x32_bf16 v[148:151], v[12:15], v[20:23], v[148:151]
	s_and_b32 s18, s50, 0x10000
	s_xor_b32 s19, s18, 0x10000
	v_add_u32_e32 v184, s18, v240
	v_or_b32_e32 v176, s18, v242
	v_bitop3_b32 v185, s50, v242, v233 bitop3:0xce
	v_add_u32_e32 v186, s19, v240
	ds_read_b128 v[156:159], v184 offset:4096
	ds_read_b128 v[160:163], v184 offset:6144
	v_mfma_f32_16x16x32_bf16 v[144:147], v[8:11], v[20:23], v[144:147]
	s_add_i32 s18, s19, s20
	v_lshl_add_u64 v[180:181], v[152:153], 0, s[0:1]
	v_mfma_f32_16x16x32_bf16 v[140:143], v[4:7], v[20:23], v[140:143]
	v_lshl_add_u64 v[182:183], v[180:181], 0, s[38:39]
	s_mov_b32 m0, s18
	v_mfma_f32_16x16x32_bf16 v[20:23], v[0:3], v[20:23], v[136:139]
	s_add_i32 s19, s18, 0x8000
	global_load_lds_dwordx4 v[182:183], off
	v_mfma_f32_16x16x32_bf16 v[132:135], v[12:15], v[16:19], v[132:135]
	v_lshl_add_u64 v[182:183], v[180:181], 0, s[82:83]
	s_add_i32 m0, s18, 0x2000
	v_mfma_f32_16x16x32_bf16 v[128:131], v[8:11], v[16:19], v[128:131]
	global_load_lds_dwordx4 v[182:183], off
	v_lshl_add_u64 v[182:183], v[180:181], 0, s[78:79]
	v_mfma_f32_16x16x32_bf16 v[124:127], v[4:7], v[16:19], v[124:127]
	s_add_i32 m0, s18, 0x4000
	v_lshl_add_u64 v[180:181], v[180:181], 0, s[2:3]
	v_mfma_f32_16x16x32_bf16 v[16:19], v[0:3], v[16:19], v[120:123]
	global_load_lds_dwordx4 v[182:183], off
	s_add_i32 m0, s18, 0x6000
	s_waitcnt lgkmcnt(1)
	v_mfma_f32_16x16x32_bf16 v[116:119], v[12:15], v[156:159], v[116:119]
	s_nop 0
	ds_read_b128 v[120:123], v184 offset:8192
	ds_read_b128 v[136:139], v184 offset:10240
	global_load_lds_dwordx4 v[180:181], off
	v_lshl_add_u64 v[180:181], v[154:155], 0, s[0:1]
	v_mfma_f32_16x16x32_bf16 v[112:115], v[8:11], v[156:159], v[112:115]
	v_lshl_add_u64 v[182:183], v[180:181], 0, s[38:39]
	s_mov_b32 m0, s19
	v_mfma_f32_16x16x32_bf16 v[108:111], v[4:7], v[156:159], v[108:111]
	global_load_lds_dwordx4 v[182:183], off
	v_lshl_add_u64 v[182:183], v[180:181], 0, s[82:83]
	v_mfma_f32_16x16x32_bf16 v[104:107], v[0:3], v[156:159], v[104:107]
	s_add_i32 m0, s18, 0xa000
	s_waitcnt lgkmcnt(2)
	v_mfma_f32_16x16x32_bf16 v[100:103], v[12:15], v[160:163], v[100:103]
	global_load_lds_dwordx4 v[182:183], off
	v_lshl_add_u64 v[182:183], v[180:181], 0, s[78:79]
	v_mfma_f32_16x16x32_bf16 v[96:99], v[8:11], v[160:163], v[96:99]
	s_add_i32 m0, s18, 0xc000
	v_lshl_add_u64 v[180:181], v[180:181], 0, s[2:3]
	v_mfma_f32_16x16x32_bf16 v[92:95], v[4:7], v[160:163], v[92:95]
	global_load_lds_dwordx4 v[182:183], off
	s_add_i32 m0, s18, 0xe000
	v_mfma_f32_16x16x32_bf16 v[88:91], v[0:3], v[160:163], v[88:91]
	global_load_lds_dwordx4 v[180:181], off
	s_waitcnt lgkmcnt(1)
	v_mfma_f32_16x16x32_bf16 v[84:87], v[12:15], v[120:123], v[84:87]
	ds_read_b128 v[156:159], v184 offset:12288
	ds_read_b128 v[160:163], v184 offset:14336
	v_mfma_f32_16x16x32_bf16 v[80:83], v[8:11], v[120:123], v[80:83]
	v_mfma_f32_16x16x32_bf16 v[76:79], v[4:7], v[120:123], v[76:79]
	v_mfma_f32_16x16x32_bf16 v[72:75], v[0:3], v[120:123], v[72:75]
	s_waitcnt lgkmcnt(2)
	v_mfma_f32_16x16x32_bf16 v[68:71], v[12:15], v[136:139], v[68:71]
	v_mfma_f32_16x16x32_bf16 v[64:67], v[8:11], v[136:139], v[64:67]
	v_mfma_f32_16x16x32_bf16 v[60:63], v[4:7], v[136:139], v[60:63]
	v_mfma_f32_16x16x32_bf16 v[56:59], v[0:3], v[136:139], v[56:59]
	s_waitcnt lgkmcnt(1)
	v_mfma_f32_16x16x32_bf16 v[52:55], v[12:15], v[156:159], v[52:55]
	ds_read_b128 v[164:167], v176 offset:33792
	ds_read_b128 v[168:171], v176 offset:35840
	ds_read_b128 v[172:175], v176 offset:37888
	ds_read_b128 v[176:179], v176 offset:39936
	ds_read_b128 v[120:123], v184 offset:1024
	ds_read_b128 v[180:183], v184 offset:3072
	v_mfma_f32_16x16x32_bf16 v[48:51], v[8:11], v[156:159], v[48:51]
	v_mfma_f32_16x16x32_bf16 v[44:47], v[4:7], v[156:159], v[44:47]
	v_mfma_f32_16x16x32_bf16 v[40:43], v[0:3], v[156:159], v[40:43]
	s_waitcnt lgkmcnt(6)
	v_mfma_f32_16x16x32_bf16 v[36:39], v[12:15], v[160:163], v[36:39]
	v_mfma_f32_16x16x32_bf16 v[32:35], v[8:11], v[160:163], v[32:35]
	v_mfma_f32_16x16x32_bf16 v[28:31], v[4:7], v[160:163], v[28:31]
	v_mfma_f32_16x16x32_bf16 v[24:27], v[0:3], v[160:163], v[24:27]
	s_waitcnt lgkmcnt(0)
	v_mfma_f32_16x16x32_bf16 v[148:151], v[164:167], v[120:123], v[148:151]
	ds_read_b128 v[0:3], v184 offset:5120
	ds_read_b128 v[4:7], v184 offset:7168
	v_mfma_f32_16x16x32_bf16 v[144:147], v[168:171], v[120:123], v[144:147]
	v_mfma_f32_16x16x32_bf16 v[140:143], v[172:175], v[120:123], v[140:143]
	v_mfma_f32_16x16x32_bf16 v[136:139], v[176:179], v[120:123], v[20:23]
	v_mfma_f32_16x16x32_bf16 v[132:135], v[164:167], v[180:183], v[132:135]
	v_mfma_f32_16x16x32_bf16 v[128:131], v[168:171], v[180:183], v[128:131]
	v_mfma_f32_16x16x32_bf16 v[124:127], v[172:175], v[180:183], v[124:127]
	v_mfma_f32_16x16x32_bf16 v[120:123], v[176:179], v[180:183], v[16:19]
	s_waitcnt lgkmcnt(1)
	v_mfma_f32_16x16x32_bf16 v[116:119], v[164:167], v[0:3], v[116:119]
	ds_read_b128 v[8:11], v184 offset:9216
	ds_read_b128 v[12:15], v184 offset:11264
	v_mfma_f32_16x16x32_bf16 v[112:115], v[168:171], v[0:3], v[112:115]
	v_mfma_f32_16x16x32_bf16 v[108:111], v[172:175], v[0:3], v[108:111]
	v_mfma_f32_16x16x32_bf16 v[104:107], v[176:179], v[0:3], v[104:107]
	s_waitcnt lgkmcnt(2)
	v_mfma_f32_16x16x32_bf16 v[100:103], v[164:167], v[4:7], v[100:103]
	v_mfma_f32_16x16x32_bf16 v[96:99], v[168:171], v[4:7], v[96:99]
	v_mfma_f32_16x16x32_bf16 v[92:95], v[172:175], v[4:7], v[92:95]
	v_mfma_f32_16x16x32_bf16 v[88:91], v[176:179], v[4:7], v[88:91]
	s_waitcnt lgkmcnt(1)
	v_mfma_f32_16x16x32_bf16 v[84:87], v[164:167], v[8:11], v[84:87]
	ds_read_b128 v[156:159], v184 offset:13312
	ds_read_b128 v[160:163], v184 offset:15360
	v_mfma_f32_16x16x32_bf16 v[80:83], v[168:171], v[8:11], v[80:83]
	v_mfma_f32_16x16x32_bf16 v[76:79], v[172:175], v[8:11], v[76:79]
	v_mfma_f32_16x16x32_bf16 v[72:75], v[176:179], v[8:11], v[72:75]
	s_waitcnt lgkmcnt(2)
	v_mfma_f32_16x16x32_bf16 v[68:71], v[164:167], v[12:15], v[68:71]
	v_mfma_f32_16x16x32_bf16 v[64:67], v[168:171], v[12:15], v[64:67]
	v_mfma_f32_16x16x32_bf16 v[60:63], v[172:175], v[12:15], v[60:63]
	v_mfma_f32_16x16x32_bf16 v[56:59], v[176:179], v[12:15], v[56:59]
	s_waitcnt lgkmcnt(1)
	v_mfma_f32_16x16x32_bf16 v[52:55], v[164:167], v[156:159], v[52:55]
	s_waitcnt vmcnt(0)
	s_waitcnt lgkmcnt(0)
	s_barrier
; #define WAIT_V(n) asm volatile("s_waitcnt vmcnt(%0)" ::"n"(n) : "memory")
;     ...
;     for (int t = 0; t < nt; ++t) {
;       const int cur = t & 1;
;       const char* sa = shm + cur * STAGE_B;
;       const char* sn = shm + (cur ^ 1) * STAGE_B;
;       const bool more = (t + 1 < nt) || (nitem < ntiles);
; #pragma unroll
;       for (int ks = 0; ks < 2; ++ks) {
; #pragma unroll
;         for (int p = 0; p < NP; ++p) {
;           const int q = ks * NP + p;
;           acc[p * 2][0] = __builtin_amdgcn_mfma_f32_16x16x32_bf16(Bq[BDBL ? ks : 0][0], Aq[q & 1][0], acc[p * 2][0], 0, 0, 0);
;           __builtin_amdgcn_sched_barrier(0);
;           if (q == 2 * NP - 1) {
;             WAIT_V(0);
;             __syncthreads();
;             if (more) {
;               if constexpr (BDBL) {
; #pragma unroll
;                 for (int n = 0; n < 4; ++n) Bq[0][n] = *(const bf16x8*)(sn + boff + (n * 2 + 0) * 1024);
;               }
; #pragma unroll
;               for (int i = 0; i < 2; ++i) Aq[0][i] = *(const bf16x8*)(sn + aoff + (i * 2 + 0) * 1024);
;             }
;           } else if (p + 1 < NP) {
; #pragma unroll
;             for (int i = 0; i < 2; ++i) Aq[(q + 1) & 1][i] = *(const bf16x8*)(sa + aoff + (((p + 1) * 2 + i) * 2 + ks) * 1024);
;           } else {
;             if constexpr (BDBL) {
; #pragma unroll
;               for (int n = 0; n < 4; ++n) Bq[1][n] = *(const bf16x8*)(sa + boff + (n * 2 + 1) * 1024);
;             }
; #pragma unroll
;             for (int i = 0; i < 2; ++i) Aq[(q + 1) & 1][i] = *(const bf16x8*)(sa + aoff + (i * 2 + 1) * 1024);
;           }
;           __builtin_amdgcn_sched_barrier(0);
; #pragma unroll
;           for (int i = 0; i < 2; ++i)
; #pragma unroll
;             for (int n = 0; n < 4; ++n)
;               if (i + n > 0)
;                 acc[p * 2 + i][n] = __builtin_amdgcn_mfma_f32_16x16x32_bf16(Bq[BDBL ? ks : 0][n], Aq[q & 1][i], acc[p * 2 + i][n], 0, 0, 0);
;           __builtin_amdgcn_sched_barrier(0);
;           if (q == GLDS_AT) {
;             if (t + 1 < nt) GLDS_STAGE(cur ^ 1, t + 1, Ab, Bb);
;             else if (nitem < ntiles) GLDS_STAGE(0, 0, nAb, nBb);
;             __builtin_amdgcn_sched_barrier(0);
;           }
	ds_read_b128 v[12:15], v185 offset:32768
	ds_read_b128 v[8:11], v185 offset:34816
	ds_read_b128 v[4:7], v185 offset:36864
	ds_read_b128 v[0:3], v185 offset:38912
	ds_read_b128 v[20:23], v186
	ds_read_b128 v[16:19], v186 offset:2048
	v_mfma_f32_16x16x32_bf16 v[48:51], v[168:171], v[156:159], v[48:51]
	v_mfma_f32_16x16x32_bf16 v[44:47], v[172:175], v[156:159], v[44:47]
	v_mfma_f32_16x16x32_bf16 v[40:43], v[176:179], v[156:159], v[40:43]
	v_mfma_f32_16x16x32_bf16 v[36:39], v[164:167], v[160:163], v[36:39]
	v_mfma_f32_16x16x32_bf16 v[32:35], v[168:171], v[160:163], v[32:35]
	v_mfma_f32_16x16x32_bf16 v[28:31], v[172:175], v[160:163], v[28:31]
	v_mfma_f32_16x16x32_bf16 v[24:27], v[176:179], v[160:163], v[24:27]
	s_add_u32 s0, s0, 0x80
	s_addc_u32 s1, s1, 0
	s_add_i32 s50, s50, 0x10000
	s_cmpk_eq_i32 s0, 0x780
	s_cbranch_scc0 .LBB0_1058
	s_waitcnt lgkmcnt(1)
	v_mfma_f32_16x16x32_bf16 v[148:151], v[12:15], v[20:23], v[148:151]
	v_add_u32_e32 v246, 0x10000, v240
	ds_read_b128 v[156:159], v246 offset:4096
	ds_read_b128 v[160:163], v246 offset:6144
	v_mfma_f32_16x16x32_bf16 v[144:147], v[8:11], v[20:23], v[144:147]
	v_mfma_f32_16x16x32_bf16 v[140:143], v[4:7], v[20:23], v[140:143]
	v_mfma_f32_16x16x32_bf16 v[20:23], v[0:3], v[20:23], v[136:139]
	s_waitcnt lgkmcnt(2)
	v_mfma_f32_16x16x32_bf16 v[152:155], v[12:15], v[16:19], v[132:135]
	v_mfma_f32_16x16x32_bf16 v[128:131], v[8:11], v[16:19], v[128:131]
	v_mfma_f32_16x16x32_bf16 v[176:179], v[4:7], v[16:19], v[124:127]
	v_mfma_f32_16x16x32_bf16 v[16:19], v[0:3], v[16:19], v[120:123]
	s_waitcnt lgkmcnt(1)
	v_mfma_f32_16x16x32_bf16 v[180:183], v[12:15], v[156:159], v[116:119]
	s_nop 2
	ds_read_b128 v[116:119], v246 offset:8192
	ds_read_b128 v[120:123], v246 offset:10240
	v_mfma_f32_16x16x32_bf16 v[112:115], v[8:11], v[156:159], v[112:115]
	v_mfma_f32_16x16x32_bf16 v[108:111], v[4:7], v[156:159], v[108:111]
	v_mfma_f32_16x16x32_bf16 v[104:107], v[0:3], v[156:159], v[104:107]
	s_waitcnt lgkmcnt(2)
	v_mfma_f32_16x16x32_bf16 v[100:103], v[12:15], v[160:163], v[100:103]
	v_mfma_f32_16x16x32_bf16 v[96:99], v[8:11], v[160:163], v[96:99]
	v_mfma_f32_16x16x32_bf16 v[184:187], v[4:7], v[160:163], v[92:95]
	v_mfma_f32_16x16x32_bf16 v[188:191], v[0:3], v[160:163], v[88:91]
	s_waitcnt lgkmcnt(1)
	v_mfma_f32_16x16x32_bf16 v[192:195], v[12:15], v[116:119], v[84:87]
	s_nop 2
	ds_read_b128 v[84:87], v246 offset:12288
	ds_read_b128 v[156:159], v246 offset:14336
	v_mfma_f32_16x16x32_bf16 v[196:199], v[8:11], v[116:119], v[80:83]
	v_mfma_f32_16x16x32_bf16 v[200:203], v[4:7], v[116:119], v[76:79]
	v_mfma_f32_16x16x32_bf16 v[204:207], v[0:3], v[116:119], v[72:75]
	s_waitcnt lgkmcnt(2)
	v_mfma_f32_16x16x32_bf16 v[208:211], v[12:15], v[120:123], v[68:71]
	v_mfma_f32_16x16x32_bf16 v[212:215], v[8:11], v[120:123], v[64:67]
	v_mfma_f32_16x16x32_bf16 v[60:63], v[4:7], v[120:123], v[60:63]
	v_mfma_f32_16x16x32_bf16 v[216:219], v[0:3], v[120:123], v[56:59]
	s_waitcnt lgkmcnt(1)
	v_mfma_f32_16x16x32_bf16 v[220:223], v[12:15], v[84:87], v[52:55]
	s_nop 2
	v_add_u32_e32 v52, 0x10400, v243
	v_add_u32_e32 v53, 0x10c00, v243
	ds_read_b128 v[56:59], v52
	ds_read_b128 v[88:91], v53
	v_add_u32_e32 v52, 0x11400, v243
	v_add_u32_e32 v53, 0x11c00, v243
	ds_read_b128 v[92:95], v52
	ds_read_b128 v[132:135], v53
	ds_read_b128 v[52:55], v246 offset:1024
	ds_read_b128 v[68:71], v246 offset:3072
	v_mfma_f32_16x16x32_bf16 v[64:67], v[8:11], v[84:87], v[48:51]
	v_mfma_f32_16x16x32_bf16 v[124:127], v[4:7], v[84:87], v[44:47]
	v_mfma_f32_16x16x32_bf16 v[136:139], v[0:3], v[84:87], v[40:43]
	s_waitcnt lgkmcnt(6)
	v_mfma_f32_16x16x32_bf16 v[164:167], v[12:15], v[156:159], v[36:39]
	v_mfma_f32_16x16x32_bf16 v[168:171], v[8:11], v[156:159], v[32:35]
	v_mfma_f32_16x16x32_bf16 v[172:175], v[4:7], v[156:159], v[28:31]
	v_mfma_f32_16x16x32_bf16 v[24:27], v[0:3], v[156:159], v[24:27]
	s_nop 1
	v_cndmask_b32_e64 v28, 0, 1, s[4:5]
	v_cmp_ne_u32_e64 s[0:1], 1, v28
	s_andn2_b64 vcc, exec, s[4:5]
	s_cbranch_vccnz .LBB0_1061
	s_mov_b32 m0, s20
	v_lshl_add_u64 v[28:29], s[12:13], 0, v[224:225]
	v_lshl_add_u64 v[32:33], v[28:29], 0, s[76:77]
	global_load_lds_dwordx4 v[28:29], off
	s_add_i32 m0, s20, 0x2000
	v_lshl_add_u64 v[34:35], v[28:29], 0, s[96:97]
	global_load_lds_dwordx4 v[32:33], off
	s_add_i32 m0, s20, 0x4000
	v_lshl_add_u64 v[36:37], v[28:29], 0, s[70:71]
	global_load_lds_dwordx4 v[34:35], off
	s_add_i32 m0, s20, 0x6000
	v_lshl_add_u64 v[30:31], s[14:15], 0, v[224:225]
	global_load_lds_dwordx4 v[36:37], off
	s_add_i32 m0, s20, 0x8000
	v_lshl_add_u64 v[38:39], v[30:31], 0, s[76:77]
	global_load_lds_dwordx4 v[30:31], off
	s_add_i32 m0, s20, 0xa000
	v_lshl_add_u64 v[40:41], v[30:31], 0, s[96:97]
	global_load_lds_dwordx4 v[38:39], off
	s_add_i32 m0, s20, 0xc000
	v_lshl_add_u64 v[42:43], v[30:31], 0, s[70:71]
	global_load_lds_dwordx4 v[40:41], off
	s_add_i32 m0, s20, 0xe000
	s_nop 0
	global_load_lds_dwordx4 v[42:43], off
